# IN epilogues (main tail k-rope replication and the 128x128 extra tiles): runs of 4 dwordx2 row stores -> permlane32_swap + 2 dwordx4 (data swapped once per 6-way replication)
# baseline (speedup 1.0000x reference)
.Lgin_nolag2:
	v_lshrrev_b32_e32 v248, 2, v200
	v_and_b32_e32 v248, 8, v248
	v_mov_b32_e32 v249, 0
	s_nop 15
	s_nop 15
	s_waitcnt lgkmcnt(3)
	s_waitcnt lgkmcnt(2)
	s_waitcnt lgkmcnt(1)
	s_waitcnt lgkmcnt(0)
	s_waitcnt lgkmcnt(0)
	v_add_u32_e32 v0, 0x12000, v172
	v_add_u32_e32 v0, 0x14400, v172
	v_add_u32_e32 v0, 0x16800, v172
	v_add_u32_e32 v0, 0x18c00, v172
	s_waitcnt lgkmcnt(3)
	s_waitcnt lgkmcnt(2)
	s_waitcnt lgkmcnt(1)
	s_waitcnt lgkmcnt(0)
	s_waitcnt lgkmcnt(0)
	v_add_u32_e32 v0, 0x1b000, v172
	v_add_u32_e32 v0, 0x1d400, v172
	v_add_u32_e32 v0, 0x1f800, v172
	v_add_u32_e32 v0, 0x21c00, v172
	s_waitcnt lgkmcnt(3)
	s_waitcnt lgkmcnt(2)
	s_waitcnt lgkmcnt(1)
	s_waitcnt lgkmcnt(0)
	s_waitcnt lgkmcnt(0)
	v_add_u32_e32 v0, 0x12000, v170
	s_waitcnt lgkmcnt(3)
	s_waitcnt lgkmcnt(2)
	s_waitcnt lgkmcnt(1)
	s_waitcnt lgkmcnt(0)
	s_waitcnt lgkmcnt(0)
	s_waitcnt lgkmcnt(1)
	s_waitcnt lgkmcnt(0)
	s_waitcnt lgkmcnt(0)
	s_waitcnt lgkmcnt(3)
	s_waitcnt lgkmcnt(2)
	s_waitcnt lgkmcnt(1)
	s_waitcnt lgkmcnt(0)
	s_waitcnt lgkmcnt(0)
	s_waitcnt lgkmcnt(3)
	s_waitcnt lgkmcnt(2)
	s_waitcnt lgkmcnt(1)
	s_waitcnt lgkmcnt(0)
	s_waitcnt lgkmcnt(0)
	s_waitcnt lgkmcnt(4)
	v_add_u32_e32 v147, s1, v233
	s_movk_i32 s1, 0x4000
	s_waitcnt lgkmcnt(0)
	v_or_b32_e32 v132, v147, v177
	v_cmp_gt_i32_e64 s[44:45], s1, v132
	v_cmp_lt_i32_e32 vcc, s24, v132
	s_and_saveexec_b64 s[2:3], vcc
	s_xor_b64 s[2:3], exec, s[2:3]
	v_add_u32_e32 v0, 0xffffc000, v147
	v_lshrrev_b32_e32 v142, 8, v0
	v_and_b32_e32 v0, 0x9f, v132
	v_or_b32_e32 v0, 0x2000, v0
	s_or_saveexec_b64 s[2:3], s[2:3]
	v_lshrrev_b32_e32 v130, 2, v147
	v_mov_b32_e32 v131, 0
	v_ashrrev_i32_e32 v146, 13, v147
	v_and_b32_e32 v148, 0x7e0, v130
	v_mov_b32_e32 v160, 0
	s_xor_b64 exec, exec, s[2:3]
	v_ashrrev_i32_e32 v142, 13, v147
	v_and_b32_e32 v0, 0x1f9f, v132
	v_and_b32_e32 v131, 0x7e0, v130
	v_mov_b32_e32 v160, v175
	s_or_b64 exec, exec, s[2:3]
	v_lshlrev_b32_e32 v134, 1, v0
	v_lshrrev_b32_e32 v135, 1, v0
	v_and_b32_e32 v133, 0x3ff3, v0
	v_and_b32_e32 v134, 8, v134
	v_and_b32_e32 v135, 4, v135
	v_and_b32_e32 v130, 0xc0, v231
	v_or3_b32 v140, v134, v133, v135
	v_ashrrev_i32_e32 v133, 31, v132
	v_or_b32_e32 v130, s0, v130
	v_lshlrev_b64 v[134:135], 8, v[132:133]
	v_lshl_add_u64 v[138:139], s[36:37], 0, v[134:135]
	v_lshlrev_b64 v[134:135], 3, v[132:133]
	v_lshlrev_b64 v[136:137], 9, v[132:133]
	v_lshlrev_b32_e32 v144, 1, v140
	v_mov_b32_e32 v145, v1
	v_ashrrev_i32_e32 v133, 5, v130
	v_or_b32_e32 v158, v131, v174
	v_or_b32_e32 v159, v131, v173
	v_or_b32_e32 v156, v131, v234
	v_or_b32_e32 v157, v131, v235
	v_or_b32_e32 v154, v160, v174
	v_or_b32_e32 v155, v160, v173
	v_or_b32_e32 v152, v160, v234
	v_or_b32_e32 v153, v160, v235
	v_mul_lo_u32 v150, v142, 6
	v_lshl_add_u64 v[136:137], v[178:179], 0, v[136:137]
	v_lshlrev_b32_e32 v149, 2, v142
	v_lshl_add_u64 v[140:141], v[180:181], 0, v[144:145]
	v_lshlrev_b32_e32 v151, 1, v142
	v_lshl_add_u64 v[142:143], v[182:183], 0, v[144:145]
	v_cmp_lt_i32_e64 s[42:43], 15, v133
	s_and_saveexec_b64 s[0:1], s[42:43]
	s_xor_b64 s[2:3], exec, s[0:1]
	s_cbranch_execz .LBB0_257
	v_cmp_lt_u32_e32 vcc, 19, v133
	s_and_saveexec_b64 s[0:1], vcc
	s_xor_b64 s[40:41], exec, s[0:1]
	s_cbranch_execz .LBB0_254
	v_cmp_lt_u32_e32 vcc, 35, v133
	s_and_saveexec_b64 s[0:1], vcc
	s_xor_b64 s[22:23], exec, s[0:1]
	s_cbranch_execz .LBB0_245
	v_cmp_lt_u32_e32 vcc, 43, v133
	s_and_saveexec_b64 s[0:1], vcc
	s_xor_b64 s[88:89], exec, s[0:1]
	s_cbranch_execz .LBB0_242
	v_cmp_lt_u32_e32 vcc, 55, v133
	s_and_saveexec_b64 s[0:1], vcc
	s_xor_b64 s[90:91], exec, s[0:1]
	s_cbranch_execz .LBB0_231
	s_movk_i32 s0, 0x700
	v_cmp_eq_u32_e32 vcc, s0, v130
	s_and_saveexec_b64 s[92:93], vcc
	s_cbranch_execz .LBB0_230
	s_and_saveexec_b64 s[94:95], s[44:45]
	s_cbranch_execz .LBB0_229
	v_lshlrev_b32_e32 v131, 3, v158
	v_lshlrev_b32_e32 v161, 3, v159
	global_load_dwordx2 v[144:145], v131, s[80:81]
	global_load_dwordx2 v[196:197], v161, s[80:81]
	v_lshlrev_b32_e32 v131, 3, v157
	s_waitcnt vmcnt(1)
	v_mov_b32_e32 v198, v144
	s_waitcnt vmcnt(0)
	v_mov_b32_e32 v199, v196
	v_mov_b32_e32 v196, v145
	v_mul_f32_e32 v144, v122, v196
	v_mul_f32_e32 v145, v123, v197
	s_nop 0
	v_fma_f32 v144, v114, v198, -v144
	v_fma_f32 v145, v115, v199, -v145
	v_mul_f32_e32 v114, v114, v196
	v_mul_f32_e32 v115, v115, v197
	s_nop 0
	v_fma_f32 v122, v122, v198, v114
	v_fma_f32 v123, v123, v199, v115
	v_lshlrev_b32_e32 v114, 3, v156
	global_load_dwordx2 v[114:115], v114, s[80:81]
	s_nop 0
	global_load_dwordx2 v[196:197], v131, s[80:81]
	s_waitcnt vmcnt(1)
	v_mov_b32_e32 v198, v114
	s_waitcnt vmcnt(0)
	v_mov_b32_e32 v199, v196
	v_mov_b32_e32 v196, v115
	v_mul_f32_e32 v114, v124, v196
	v_mul_f32_e32 v115, v125, v197
	s_nop 0
	v_fma_f32 v208, v116, v198, -v114
	v_fma_f32 v209, v117, v199, -v115
	v_mul_f32_e32 v114, v116, v196
	v_mul_f32_e32 v115, v117, v197
	v_lshlrev_b32_e32 v116, 3, v155
	v_fma_f32 v124, v124, v198, v114
	v_fma_f32 v125, v125, v199, v115
	v_lshlrev_b32_e32 v114, 3, v154
	global_load_dwordx2 v[114:115], v114, s[80:81]
	s_nop 0
	global_load_dwordx2 v[116:117], v116, s[80:81]
	s_waitcnt vmcnt(1)
	v_mov_b32_e32 v196, v114
	s_waitcnt vmcnt(0)
	v_mov_b32_e32 v197, v116
	v_mov_b32_e32 v116, v115
	v_mul_f32_e32 v114, v126, v116
	v_mul_f32_e32 v115, v127, v117
	s_nop 0
	v_fma_f32 v198, v118, v196, -v114
	v_fma_f32 v199, v119, v197, -v115
	v_mul_f32_e32 v114, v118, v116
	v_mul_f32_e32 v115, v119, v117
	v_lshlrev_b32_e32 v116, 3, v152
	v_fma_f32 v126, v126, v196, v114
	v_fma_f32 v127, v127, v197, v115
	v_lshlrev_b32_e32 v114, 3, v153
	global_load_dwordx2 v[114:115], v114, s[80:81]
	s_nop 0
	global_load_dwordx2 v[116:117], v116, s[80:81]
	s_waitcnt vmcnt(1)
	v_mov_b32_e32 v197, v115
	s_waitcnt vmcnt(0)
	v_mov_b32_e32 v196, v117
	v_mov_b32_e32 v118, v116
	v_mov_b32_e32 v119, v114
	v_mul_f32_e32 v196, v128, v196
	v_mul_f32_e32 v197, v129, v197
	v_mul_f32_e32 v116, v128, v116
	v_fma_f32 v196, v120, v118, -v196
	v_fma_f32 v197, v121, v119, -v197
	v_mul_f32_e32 v118, v120, v117
	v_mov_b32_e32 v120, v129
	v_mul_f32_e32 v114, v120, v114
	v_mul_f32_e32 v115, v121, v115
	v_mov_b32_e32 v120, v196
	v_mov_b32_e32 v117, v114
	v_mov_b32_e32 v119, v115
	v_add_f32_e32 v128, v116, v118
	v_add_f32_e32 v129, v117, v119
	v_mov_b32_e32 v114, v144
	v_mov_b32_e32 v115, v145
	v_mov_b32_e32 v116, v208
	v_mov_b32_e32 v117, v209
	v_mov_b32_e32 v118, v198
	v_mov_b32_e32 v119, v199
	v_mov_b32_e32 v121, v197
.LBB0_229:
	s_or_b64 exec, exec, s[94:95]
	v_cvt_pk_bf16_f32 v114, v114, v115
	v_cvt_pk_bf16_f32 v115, v116, v117
	v_cvt_pk_bf16_f32 v116, v118, v119
	v_cvt_pk_bf16_f32 v118, v122, v123
	v_cvt_pk_bf16_f32 v119, v124, v125
	v_mad_i64_i32 v[122:123], s[0:1], v150, s25, v[0:1]
	v_mov_b64_e32 v[124:125], s[36:37]
	v_cvt_pk_bf16_f32 v117, v120, v121
	v_cvt_pk_bf16_f32 v120, v126, v127
	v_mad_u64_u32 v[126:127], s[0:1], v122, s5, v[124:125]
	v_mad_i32_i24 v127, v123, s5, v127
	v_lshlrev_b32_e32 v122, 1, v176
	v_mov_b32_e32 v123, v1
	v_lshl_add_u64 v[126:127], v[126:127], 0, v[122:123]
	s_mov_b64 s[12:13], 0x917d880
	v_cvt_pk_bf16_f32 v121, v128, v129
	v_lshl_add_u64 v[128:129], v[126:127], 0, s[12:13]
	v_add_co_u32_e32 v126, vcc, s47, v126
	s_nop 1
	v_addc_co_u32_e32 v127, vcc, 0, v127, vcc
	s_nop 1
	v_permlane32_swap_b32 v114, v116
	v_permlane32_swap_b32 v115, v117
	v_permlane32_swap_b32 v118, v120
	v_permlane32_swap_b32 v119, v121
	v_lshl_add_u64 v[250:251], v[128:129], 0, v[248:249]
	global_store_dwordx4 v[250:251], v[114:117], off
	global_store_dwordx4 v[250:251], v[118:121], off offset:32
	v_or_b32_e32 v126, 1, v150
	v_mad_i64_i32 v[126:127], s[0:1], v126, s25, v[0:1]
	v_mad_u64_u32 v[128:129], s[0:1], v126, s5, v[124:125]
	v_mad_i32_i24 v129, v127, s5, v129
	v_lshl_add_u64 v[126:127], v[128:129], 0, v[122:123]
	v_lshl_add_u64 v[128:129], v[126:127], 0, s[12:13]
	v_add_co_u32_e32 v126, vcc, s47, v126
	s_nop 1
	v_addc_co_u32_e32 v127, vcc, 0, v127, vcc
	v_lshl_add_u64 v[250:251], v[128:129], 0, v[248:249]
	global_store_dwordx4 v[250:251], v[114:117], off
	global_store_dwordx4 v[250:251], v[118:121], off offset:32
	v_add_u32_e32 v126, 2, v150
	v_mad_i64_i32 v[126:127], s[0:1], v126, s25, v[0:1]
	v_mad_u64_u32 v[128:129], s[0:1], v126, s5, v[124:125]
	v_mad_i32_i24 v129, v127, s5, v129
	v_lshl_add_u64 v[126:127], v[128:129], 0, v[122:123]
	v_lshl_add_u64 v[128:129], v[126:127], 0, s[12:13]
	v_add_co_u32_e32 v126, vcc, s47, v126
	s_nop 1
	v_addc_co_u32_e32 v127, vcc, 0, v127, vcc
	v_lshl_add_u64 v[250:251], v[128:129], 0, v[248:249]
	global_store_dwordx4 v[250:251], v[114:117], off
	global_store_dwordx4 v[250:251], v[118:121], off offset:32
	v_add_u32_e32 v126, 3, v150
	v_mad_i64_i32 v[126:127], s[0:1], v126, s25, v[0:1]
	v_mad_u64_u32 v[128:129], s[0:1], v126, s5, v[124:125]
	v_mad_i32_i24 v129, v127, s5, v129
	v_lshl_add_u64 v[126:127], v[128:129], 0, v[122:123]
	v_lshl_add_u64 v[128:129], v[126:127], 0, s[12:13]
	v_add_co_u32_e32 v126, vcc, s47, v126
	s_nop 1
	v_addc_co_u32_e32 v127, vcc, 0, v127, vcc
	v_lshl_add_u64 v[250:251], v[128:129], 0, v[248:249]
	global_store_dwordx4 v[250:251], v[114:117], off
	global_store_dwordx4 v[250:251], v[118:121], off offset:32
	v_add_u32_e32 v126, 4, v150
	v_mad_i64_i32 v[126:127], s[0:1], v126, s25, v[0:1]
	v_mad_u64_u32 v[128:129], s[0:1], v126, s5, v[124:125]
	v_mad_i32_i24 v129, v127, s5, v129
	v_lshl_add_u64 v[126:127], v[128:129], 0, v[122:123]
	v_lshl_add_u64 v[128:129], v[126:127], 0, s[12:13]
	v_add_co_u32_e32 v126, vcc, s47, v126
	s_nop 1
	v_addc_co_u32_e32 v127, vcc, 0, v127, vcc
	v_lshl_add_u64 v[250:251], v[128:129], 0, v[248:249]
	global_store_dwordx4 v[250:251], v[114:117], off
	global_store_dwordx4 v[250:251], v[118:121], off offset:32
	v_add_u32_e32 v126, 5, v150
	v_mad_i64_i32 v[126:127], s[0:1], v126, s25, v[0:1]
	v_mad_u64_u32 v[124:125], s[0:1], v126, s5, v[124:125]
	v_mad_i32_i24 v125, v127, s5, v125
	v_lshl_add_u64 v[122:123], v[124:125], 0, v[122:123]
	v_lshl_add_u64 v[124:125], v[122:123], 0, s[12:13]
	v_add_co_u32_e32 v122, vcc, 0x917d000, v122
	s_nop 1
	v_addc_co_u32_e32 v123, vcc, 0, v123, vcc
	v_lshl_add_u64 v[250:251], v[124:125], 0, v[248:249]
	global_store_dwordx4 v[250:251], v[114:117], off
	global_store_dwordx4 v[250:251], v[118:121], off offset:32

.LBB0_316:
	s_or_b64 exec, exec, vcc
	v_cvt_pk_bf16_f32 v82, v82, v83
	v_cvt_pk_bf16_f32 v83, v84, v85
	v_cvt_pk_bf16_f32 v84, v86, v87
	v_cvt_pk_bf16_f32 v86, v90, v91
	v_cvt_pk_bf16_f32 v87, v92, v93
	v_mad_i64_i32 v[90:91], s[0:1], v111, s25, v[0:1]
	v_mov_b64_e32 v[92:93], s[36:37]
	v_cvt_pk_bf16_f32 v85, v88, v89
	v_cvt_pk_bf16_f32 v88, v94, v95
	v_mad_u64_u32 v[94:95], s[0:1], v90, s5, v[92:93]
	v_mad_i32_i24 v95, v91, s5, v95
	v_lshlrev_b32_e32 v90, 1, v176
	v_mov_b32_e32 v91, v1
	v_lshl_add_u64 v[94:95], v[94:95], 0, v[90:91]
	s_mov_b64 s[12:13], 0x917d880
	v_cvt_pk_bf16_f32 v89, v96, v97
	v_lshl_add_u64 v[96:97], v[94:95], 0, s[12:13]
	v_add_co_u32_e32 v94, vcc, s47, v94
	s_nop 1
	v_addc_co_u32_e32 v95, vcc, 0, v95, vcc
	s_nop 1
	v_permlane32_swap_b32 v82, v84
	v_permlane32_swap_b32 v83, v85
	v_permlane32_swap_b32 v86, v88
	v_permlane32_swap_b32 v87, v89
	v_lshl_add_u64 v[250:251], v[96:97], 0, v[248:249]
	global_store_dwordx4 v[250:251], v[82:85], off
	global_store_dwordx4 v[250:251], v[86:89], off offset:32
	v_or_b32_e32 v94, 1, v111
	v_mad_i64_i32 v[94:95], s[0:1], v94, s25, v[0:1]
	v_mad_u64_u32 v[96:97], s[0:1], v94, s5, v[92:93]
	v_mad_i32_i24 v97, v95, s5, v97
	v_lshl_add_u64 v[94:95], v[96:97], 0, v[90:91]
	v_lshl_add_u64 v[96:97], v[94:95], 0, s[12:13]
	v_add_co_u32_e32 v94, vcc, s47, v94
	s_nop 1
	v_addc_co_u32_e32 v95, vcc, 0, v95, vcc
	v_lshl_add_u64 v[250:251], v[96:97], 0, v[248:249]
	global_store_dwordx4 v[250:251], v[82:85], off
	global_store_dwordx4 v[250:251], v[86:89], off offset:32
	v_add_u32_e32 v94, 2, v111
	v_mad_i64_i32 v[94:95], s[0:1], v94, s25, v[0:1]
	v_mad_u64_u32 v[96:97], s[0:1], v94, s5, v[92:93]
	v_mad_i32_i24 v97, v95, s5, v97
	v_lshl_add_u64 v[94:95], v[96:97], 0, v[90:91]
	v_lshl_add_u64 v[96:97], v[94:95], 0, s[12:13]
	v_add_co_u32_e32 v94, vcc, s47, v94
	s_nop 1
	v_addc_co_u32_e32 v95, vcc, 0, v95, vcc
	v_lshl_add_u64 v[250:251], v[96:97], 0, v[248:249]
	global_store_dwordx4 v[250:251], v[82:85], off
	global_store_dwordx4 v[250:251], v[86:89], off offset:32
	v_add_u32_e32 v94, 3, v111
	v_mad_i64_i32 v[94:95], s[0:1], v94, s25, v[0:1]
	v_mad_u64_u32 v[96:97], s[0:1], v94, s5, v[92:93]
	v_mad_i32_i24 v97, v95, s5, v97
	v_lshl_add_u64 v[94:95], v[96:97], 0, v[90:91]
	v_lshl_add_u64 v[96:97], v[94:95], 0, s[12:13]
	v_add_co_u32_e32 v94, vcc, s47, v94
	s_nop 1
	v_addc_co_u32_e32 v95, vcc, 0, v95, vcc
	v_lshl_add_u64 v[250:251], v[96:97], 0, v[248:249]
	global_store_dwordx4 v[250:251], v[82:85], off
	global_store_dwordx4 v[250:251], v[86:89], off offset:32
	v_add_u32_e32 v94, 4, v111
	v_mad_i64_i32 v[94:95], s[0:1], v94, s25, v[0:1]
	v_mad_u64_u32 v[96:97], s[0:1], v94, s5, v[92:93]
	v_mad_i32_i24 v97, v95, s5, v97
	v_lshl_add_u64 v[94:95], v[96:97], 0, v[90:91]
	v_lshl_add_u64 v[96:97], v[94:95], 0, s[12:13]
	v_add_co_u32_e32 v94, vcc, s47, v94
	s_nop 1
	v_addc_co_u32_e32 v95, vcc, 0, v95, vcc
	v_lshl_add_u64 v[250:251], v[96:97], 0, v[248:249]
	global_store_dwordx4 v[250:251], v[82:85], off
	global_store_dwordx4 v[250:251], v[86:89], off offset:32
	v_add_u32_e32 v94, 5, v111
	v_mad_i64_i32 v[94:95], s[0:1], v94, s25, v[0:1]
	v_mad_u64_u32 v[92:93], s[0:1], v94, s5, v[92:93]
	v_mad_i32_i24 v93, v95, s5, v93
	v_lshl_add_u64 v[90:91], v[92:93], 0, v[90:91]
	v_lshl_add_u64 v[92:93], v[90:91], 0, s[12:13]
	v_add_co_u32_e32 v90, vcc, 0x917d000, v90
	s_nop 1
	v_addc_co_u32_e32 v91, vcc, 0, v91, vcc
	v_lshl_add_u64 v[250:251], v[92:93], 0, v[248:249]
	global_store_dwordx4 v[250:251], v[82:85], off
	global_store_dwordx4 v[250:251], v[86:89], off offset:32

.LBB0_400:
	s_or_b64 exec, exec, vcc
	v_cvt_pk_bf16_f32 v50, v50, v51
	v_cvt_pk_bf16_f32 v51, v52, v53
	v_cvt_pk_bf16_f32 v52, v54, v55
	v_cvt_pk_bf16_f32 v54, v58, v59
	v_cvt_pk_bf16_f32 v55, v60, v61
	v_mad_i64_i32 v[58:59], s[0:1], v79, s25, v[0:1]
	v_mov_b64_e32 v[60:61], s[36:37]
	v_cvt_pk_bf16_f32 v53, v56, v57
	v_cvt_pk_bf16_f32 v56, v62, v63
	v_mad_u64_u32 v[62:63], s[0:1], v58, s5, v[60:61]
	v_mad_i32_i24 v63, v59, s5, v63
	v_lshlrev_b32_e32 v58, 1, v176
	v_mov_b32_e32 v59, v1
	v_lshl_add_u64 v[62:63], v[62:63], 0, v[58:59]
	s_mov_b64 s[12:13], 0x917d880
	v_cvt_pk_bf16_f32 v57, v64, v65
	v_lshl_add_u64 v[64:65], v[62:63], 0, s[12:13]
	v_add_co_u32_e32 v62, vcc, s47, v62
	s_nop 1
	v_addc_co_u32_e32 v63, vcc, 0, v63, vcc
	s_nop 1
	v_permlane32_swap_b32 v50, v52
	v_permlane32_swap_b32 v51, v53
	v_permlane32_swap_b32 v54, v56
	v_permlane32_swap_b32 v55, v57
	v_lshl_add_u64 v[250:251], v[64:65], 0, v[248:249]
	global_store_dwordx4 v[250:251], v[50:53], off
	global_store_dwordx4 v[250:251], v[54:57], off offset:32
	v_or_b32_e32 v62, 1, v79
	v_mad_i64_i32 v[62:63], s[0:1], v62, s25, v[0:1]
	v_mad_u64_u32 v[64:65], s[0:1], v62, s5, v[60:61]
	v_mad_i32_i24 v65, v63, s5, v65
	v_lshl_add_u64 v[62:63], v[64:65], 0, v[58:59]
	v_lshl_add_u64 v[64:65], v[62:63], 0, s[12:13]
	v_add_co_u32_e32 v62, vcc, s47, v62
	s_nop 1
	v_addc_co_u32_e32 v63, vcc, 0, v63, vcc
	v_lshl_add_u64 v[250:251], v[64:65], 0, v[248:249]
	global_store_dwordx4 v[250:251], v[50:53], off
	global_store_dwordx4 v[250:251], v[54:57], off offset:32
	v_add_u32_e32 v62, 2, v79
	v_mad_i64_i32 v[62:63], s[0:1], v62, s25, v[0:1]
	v_mad_u64_u32 v[64:65], s[0:1], v62, s5, v[60:61]
	v_mad_i32_i24 v65, v63, s5, v65
	v_lshl_add_u64 v[62:63], v[64:65], 0, v[58:59]
	v_lshl_add_u64 v[64:65], v[62:63], 0, s[12:13]
	v_add_co_u32_e32 v62, vcc, s47, v62
	s_nop 1
	v_addc_co_u32_e32 v63, vcc, 0, v63, vcc
	v_lshl_add_u64 v[250:251], v[64:65], 0, v[248:249]
	global_store_dwordx4 v[250:251], v[50:53], off
	global_store_dwordx4 v[250:251], v[54:57], off offset:32
	v_add_u32_e32 v62, 3, v79
	v_mad_i64_i32 v[62:63], s[0:1], v62, s25, v[0:1]
	v_mad_u64_u32 v[64:65], s[0:1], v62, s5, v[60:61]
	v_mad_i32_i24 v65, v63, s5, v65
	v_lshl_add_u64 v[62:63], v[64:65], 0, v[58:59]
	v_lshl_add_u64 v[64:65], v[62:63], 0, s[12:13]
	v_add_co_u32_e32 v62, vcc, s47, v62
	s_nop 1
	v_addc_co_u32_e32 v63, vcc, 0, v63, vcc
	v_lshl_add_u64 v[250:251], v[64:65], 0, v[248:249]
	global_store_dwordx4 v[250:251], v[50:53], off
	global_store_dwordx4 v[250:251], v[54:57], off offset:32
	v_add_u32_e32 v62, 4, v79
	v_mad_i64_i32 v[62:63], s[0:1], v62, s25, v[0:1]
	v_mad_u64_u32 v[64:65], s[0:1], v62, s5, v[60:61]
	v_mad_i32_i24 v65, v63, s5, v65
	v_lshl_add_u64 v[62:63], v[64:65], 0, v[58:59]
	v_lshl_add_u64 v[64:65], v[62:63], 0, s[12:13]
	v_add_co_u32_e32 v62, vcc, s47, v62
	s_nop 1
	v_addc_co_u32_e32 v63, vcc, 0, v63, vcc
	v_lshl_add_u64 v[250:251], v[64:65], 0, v[248:249]
	global_store_dwordx4 v[250:251], v[50:53], off
	global_store_dwordx4 v[250:251], v[54:57], off offset:32
	v_add_u32_e32 v62, 5, v79
	v_mad_i64_i32 v[62:63], s[0:1], v62, s25, v[0:1]
	v_mad_u64_u32 v[60:61], s[0:1], v62, s5, v[60:61]
	v_mad_i32_i24 v61, v63, s5, v61
	v_lshl_add_u64 v[58:59], v[60:61], 0, v[58:59]
	v_lshl_add_u64 v[60:61], v[58:59], 0, s[12:13]
	v_add_co_u32_e32 v58, vcc, 0x917d000, v58
	s_nop 1
	v_addc_co_u32_e32 v59, vcc, 0, v59, vcc
	v_lshl_add_u64 v[250:251], v[60:61], 0, v[248:249]
	global_store_dwordx4 v[250:251], v[50:53], off
	global_store_dwordx4 v[250:251], v[54:57], off offset:32

.LBB0_484:
	s_or_b64 exec, exec, s[94:95]
	v_cvt_pk_bf16_f32 v18, v18, v19
	v_cvt_pk_bf16_f32 v19, v20, v21
	v_cvt_pk_bf16_f32 v20, v22, v23
	v_cvt_pk_bf16_f32 v22, v26, v27
	v_cvt_pk_bf16_f32 v23, v28, v29
	v_mad_i64_i32 v[26:27], s[0:1], v47, s25, v[0:1]
	v_mov_b64_e32 v[28:29], s[36:37]
	v_cvt_pk_bf16_f32 v21, v24, v25
	v_cvt_pk_bf16_f32 v24, v30, v31
	v_mad_u64_u32 v[30:31], s[0:1], v26, s5, v[28:29]
	v_mad_i32_i24 v31, v27, s5, v31
	v_lshlrev_b32_e32 v26, 1, v176
	v_mov_b32_e32 v27, v1
	v_lshl_add_u64 v[30:31], v[30:31], 0, v[26:27]
	s_mov_b64 s[12:13], 0x917d880
	v_cvt_pk_bf16_f32 v25, v32, v33
	v_lshl_add_u64 v[32:33], v[30:31], 0, s[12:13]
	v_add_co_u32_e32 v30, vcc, s47, v30
	s_nop 1
	v_addc_co_u32_e32 v31, vcc, 0, v31, vcc
	s_nop 1
	v_permlane32_swap_b32 v18, v20
	v_permlane32_swap_b32 v19, v21
	v_permlane32_swap_b32 v22, v24
	v_permlane32_swap_b32 v23, v25
	v_lshl_add_u64 v[250:251], v[32:33], 0, v[248:249]
	global_store_dwordx4 v[250:251], v[18:21], off
	global_store_dwordx4 v[250:251], v[22:25], off offset:32
	v_or_b32_e32 v30, 1, v47
	v_mad_i64_i32 v[30:31], s[0:1], v30, s25, v[0:1]
	v_mad_u64_u32 v[32:33], s[0:1], v30, s5, v[28:29]
	v_mad_i32_i24 v33, v31, s5, v33
	v_lshl_add_u64 v[30:31], v[32:33], 0, v[26:27]
	v_lshl_add_u64 v[32:33], v[30:31], 0, s[12:13]
	v_add_co_u32_e32 v30, vcc, s47, v30
	s_nop 1
	v_addc_co_u32_e32 v31, vcc, 0, v31, vcc
	v_lshl_add_u64 v[250:251], v[32:33], 0, v[248:249]
	global_store_dwordx4 v[250:251], v[18:21], off
	global_store_dwordx4 v[250:251], v[22:25], off offset:32
	v_add_u32_e32 v30, 2, v47
	v_mad_i64_i32 v[30:31], s[0:1], v30, s25, v[0:1]
	v_mad_u64_u32 v[32:33], s[0:1], v30, s5, v[28:29]
	v_mad_i32_i24 v33, v31, s5, v33
	v_lshl_add_u64 v[30:31], v[32:33], 0, v[26:27]
	v_lshl_add_u64 v[32:33], v[30:31], 0, s[12:13]
	v_add_co_u32_e32 v30, vcc, s47, v30
	s_nop 1
	v_addc_co_u32_e32 v31, vcc, 0, v31, vcc
	v_lshl_add_u64 v[250:251], v[32:33], 0, v[248:249]
	global_store_dwordx4 v[250:251], v[18:21], off
	global_store_dwordx4 v[250:251], v[22:25], off offset:32
	v_add_u32_e32 v30, 3, v47
	v_mad_i64_i32 v[30:31], s[0:1], v30, s25, v[0:1]
	v_mad_u64_u32 v[32:33], s[0:1], v30, s5, v[28:29]
	v_mad_i32_i24 v33, v31, s5, v33
	v_lshl_add_u64 v[30:31], v[32:33], 0, v[26:27]
	v_lshl_add_u64 v[32:33], v[30:31], 0, s[12:13]
	v_add_co_u32_e32 v30, vcc, s47, v30
	s_nop 1
	v_addc_co_u32_e32 v31, vcc, 0, v31, vcc
	v_lshl_add_u64 v[250:251], v[32:33], 0, v[248:249]
	global_store_dwordx4 v[250:251], v[18:21], off
	global_store_dwordx4 v[250:251], v[22:25], off offset:32
	v_add_u32_e32 v30, 4, v47
	v_mad_i64_i32 v[30:31], s[0:1], v30, s25, v[0:1]
	v_mad_u64_u32 v[32:33], s[0:1], v30, s5, v[28:29]
	v_mad_i32_i24 v33, v31, s5, v33
	v_lshl_add_u64 v[30:31], v[32:33], 0, v[26:27]
	v_lshl_add_u64 v[32:33], v[30:31], 0, s[12:13]
	v_add_co_u32_e32 v30, vcc, s47, v30
	s_nop 1
	v_addc_co_u32_e32 v31, vcc, 0, v31, vcc
	v_lshl_add_u64 v[250:251], v[32:33], 0, v[248:249]
	global_store_dwordx4 v[250:251], v[18:21], off
	global_store_dwordx4 v[250:251], v[22:25], off offset:32
	v_add_u32_e32 v30, 5, v47
	v_mad_i64_i32 v[30:31], s[0:1], v30, s25, v[0:1]
	v_mad_u64_u32 v[28:29], s[0:1], v30, s5, v[28:29]
	v_mad_i32_i24 v29, v31, s5, v29
	v_lshl_add_u64 v[26:27], v[28:29], 0, v[26:27]
	v_lshl_add_u64 v[28:29], v[26:27], 0, s[12:13]
	v_add_co_u32_e32 v26, vcc, 0x917d000, v26
	s_nop 1
	v_addc_co_u32_e32 v27, vcc, 0, v27, vcc
	v_lshl_add_u64 v[250:251], v[28:29], 0, v[248:249]
	global_store_dwordx4 v[250:251], v[18:21], off
	global_store_dwordx4 v[250:251], v[22:25], off offset:32

.LBB0_554:
	s_or_b64 exec, exec, s[22:23]
	v_mul_lo_u32 v18, v36, 6
	v_cvt_pk_bf16_f32 v2, v2, v3
	v_cvt_pk_bf16_f32 v3, v4, v5
	v_cvt_pk_bf16_f32 v4, v6, v7
	v_cvt_pk_bf16_f32 v6, v10, v11
	v_cvt_pk_bf16_f32 v7, v12, v13
	v_mad_i64_i32 v[10:11], s[0:1], v18, s25, v[0:1]
	v_mov_b64_e32 v[12:13], s[36:37]
	v_cvt_pk_bf16_f32 v5, v8, v9
	v_cvt_pk_bf16_f32 v8, v14, v15
	v_mad_u64_u32 v[14:15], s[0:1], v10, s5, v[12:13]
	v_mad_i32_i24 v15, v11, s5, v15
	v_lshlrev_b32_e32 v10, 1, v37
	v_mov_b32_e32 v11, v1
	v_lshl_add_u64 v[14:15], v[14:15], 0, v[10:11]
	v_cvt_pk_bf16_f32 v9, v16, v17
	v_lshl_add_u64 v[16:17], v[14:15], 0, s[8:9]
	v_add_co_u32_e32 v14, vcc, s47, v14
	s_nop 1
	v_addc_co_u32_e32 v15, vcc, 0, v15, vcc
	s_nop 1
	v_permlane32_swap_b32 v2, v4
	v_permlane32_swap_b32 v3, v5
	v_permlane32_swap_b32 v6, v8
	v_permlane32_swap_b32 v7, v9
	v_lshl_add_u64 v[250:251], v[16:17], 0, v[248:249]
	global_store_dwordx4 v[250:251], v[2:5], off
	global_store_dwordx4 v[250:251], v[6:9], off offset:32
	v_or_b32_e32 v14, 1, v18
	v_mad_i64_i32 v[14:15], s[0:1], v14, s25, v[0:1]
	v_mad_u64_u32 v[16:17], s[0:1], v14, s5, v[12:13]
	v_mad_i32_i24 v17, v15, s5, v17
	v_lshl_add_u64 v[14:15], v[16:17], 0, v[10:11]
	v_lshl_add_u64 v[16:17], v[14:15], 0, s[8:9]
	v_add_co_u32_e32 v14, vcc, s47, v14
	s_nop 1
	v_addc_co_u32_e32 v15, vcc, 0, v15, vcc
	v_lshl_add_u64 v[250:251], v[16:17], 0, v[248:249]
	global_store_dwordx4 v[250:251], v[2:5], off
	global_store_dwordx4 v[250:251], v[6:9], off offset:32
	v_add_u32_e32 v14, 2, v18
	v_mad_i64_i32 v[14:15], s[0:1], v14, s25, v[0:1]
	v_mad_u64_u32 v[16:17], s[0:1], v14, s5, v[12:13]
	v_mad_i32_i24 v17, v15, s5, v17
	v_lshl_add_u64 v[14:15], v[16:17], 0, v[10:11]
	v_lshl_add_u64 v[16:17], v[14:15], 0, s[8:9]
	v_add_co_u32_e32 v14, vcc, s47, v14
	s_nop 1
	v_addc_co_u32_e32 v15, vcc, 0, v15, vcc
	v_lshl_add_u64 v[250:251], v[16:17], 0, v[248:249]
	global_store_dwordx4 v[250:251], v[2:5], off
	global_store_dwordx4 v[250:251], v[6:9], off offset:32
	v_add_u32_e32 v14, 3, v18
	v_mad_i64_i32 v[14:15], s[0:1], v14, s25, v[0:1]
	v_mad_u64_u32 v[16:17], s[0:1], v14, s5, v[12:13]
	v_mad_i32_i24 v17, v15, s5, v17
	v_lshl_add_u64 v[14:15], v[16:17], 0, v[10:11]
	v_lshl_add_u64 v[16:17], v[14:15], 0, s[8:9]
	v_add_co_u32_e32 v14, vcc, s47, v14
	s_nop 1
	v_addc_co_u32_e32 v15, vcc, 0, v15, vcc
	v_lshl_add_u64 v[250:251], v[16:17], 0, v[248:249]
	global_store_dwordx4 v[250:251], v[2:5], off
	global_store_dwordx4 v[250:251], v[6:9], off offset:32
	v_add_u32_e32 v14, 4, v18
	v_mad_i64_i32 v[14:15], s[0:1], v14, s25, v[0:1]
	v_mad_u64_u32 v[16:17], s[0:1], v14, s5, v[12:13]
	v_mad_i32_i24 v17, v15, s5, v17
	v_lshl_add_u64 v[14:15], v[16:17], 0, v[10:11]
	v_lshl_add_u64 v[16:17], v[14:15], 0, s[8:9]
	v_add_co_u32_e32 v14, vcc, s47, v14
	s_nop 1
	v_addc_co_u32_e32 v15, vcc, 0, v15, vcc
	v_lshl_add_u64 v[250:251], v[16:17], 0, v[248:249]
	global_store_dwordx4 v[250:251], v[2:5], off
	global_store_dwordx4 v[250:251], v[6:9], off offset:32
	v_add_u32_e32 v14, 5, v18
	v_mad_i64_i32 v[14:15], s[0:1], v14, s25, v[0:1]
	v_mad_u64_u32 v[12:13], s[0:1], v14, s5, v[12:13]
	v_mad_i32_i24 v13, v15, s5, v13
	v_lshl_add_u64 v[10:11], v[12:13], 0, v[10:11]
	v_lshl_add_u64 v[12:13], v[10:11], 0, s[8:9]
	v_add_co_u32_e32 v10, vcc, 0x917d000, v10
	s_nop 1
	v_addc_co_u32_e32 v11, vcc, 0, v11, vcc
	v_lshl_add_u64 v[250:251], v[12:13], 0, v[248:249]
	global_store_dwordx4 v[250:251], v[2:5], off
	global_store_dwordx4 v[250:251], v[6:9], off offset:32

.LBB0_556:
	v_lshrrev_b32_e32 v248, 2, v200
	v_and_b32_e32 v248, 8, v248
	v_mov_b32_e32 v249, 0
	v_and_b32_e32 v52, 0xff, v200
	s_movk_i32 s2, 0x4000
	v_ashrrev_i32_e32 v48, 3, v52
	v_add3_u32 v2, v51, v48, s2
	v_ashrrev_i32_e32 v3, 31, v2
	v_lshlrev_b64 v[2:3], 11, v[2:3]
	v_lshlrev_b32_e32 v0, 4, v52
	v_and_b32_e32 v0, 0x70, v0
	v_lshl_add_u64 v[2:3], s[82:83], 0, v[2:3]
	v_lshl_add_u64 v[34:35], v[2:3], 0, v[0:1]
	s_mov_b32 s0, 0x10000
	v_ashrrev_i32_e32 v49, 31, v48
	v_add_co_u32_e32 v36, vcc, s0, v34
	v_lshlrev_b64 v[4:5], 11, v[48:49]
	s_nop 0
	v_addc_co_u32_e32 v37, vcc, 0, v35, vcc
	v_lshl_add_u64 v[4:5], s[84:85], 0, v[4:5]
	v_add_co_u32_e32 v38, vcc, s7, v34
	v_lshl_add_u64 v[56:57], v[4:5], 0, v[0:1]
	s_nop 0
	v_addc_co_u32_e32 v39, vcc, 0, v35, vcc
	s_mov_b32 s0, 0x380000
	v_add_co_u32_e32 v14, vcc, s0, v56
	s_mov_b32 s0, 0x390000
	s_nop 0
	v_addc_co_u32_e32 v15, vcc, 0, v57, vcc
	v_add_co_u32_e32 v40, vcc, s0, v56
	s_mov_b32 s0, 0x3a0000
	s_nop 0
	v_addc_co_u32_e32 v41, vcc, 0, v57, vcc
	global_load_dwordx4 v[2:5], v[34:35], off
	global_load_dwordx4 v[6:9], v[36:37], off
	global_load_dwordx4 v[10:13], v[38:39], off
	s_nop 0
	global_load_dwordx4 v[14:17], v[14:15], off
	s_nop 0
	global_load_dwordx4 v[18:21], v[40:41], off
	v_add_co_u32_e32 v42, vcc, s0, v56
	s_mov_b32 s0, 0x3b0000
	s_nop 0
	v_addc_co_u32_e32 v43, vcc, 0, v57, vcc
	v_add_co_u32_e32 v44, vcc, s0, v56
	global_load_dwordx4 v[22:25], v[42:43], off
	s_nop 0
	v_addc_co_u32_e32 v45, vcc, 0, v57, vcc
	global_load_dwordx4 v[26:29], v[44:45], off
	v_add_co_u32_e32 v46, vcc, s54, v34
	v_lshrrev_b32_e32 v49, 1, v52
	s_nop 0
	v_addc_co_u32_e32 v47, vcc, 0, v35, vcc
	global_load_dwordx4 v[30:33], v[46:47], off
	v_and_b32_e32 v54, 0x5f, v52
	v_mul_lo_u32 v48, v48, s4
	v_and_b32_e32 v122, 16, v49
	v_mul_u32_u24_e32 v49, 0x90, v54
	s_mov_b64 s[0:1], 0x380000
	v_add3_u32 v54, v48, v0, v232
	v_add3_u32 v0, v49, v122, v232
	v_lshl_add_u64 v[48:49], v[56:57], 0, s[0:1]
	global_load_dwordx4 v[58:61], v[34:35], off offset:128
	global_load_dwordx4 v[62:65], v[42:43], off offset:128
	global_load_dwordx4 v[66:69], v[44:45], off offset:128
	global_load_dwordx4 v[70:73], v[44:45], off offset:256
	global_load_dwordx4 v[74:77], v[42:43], off offset:256
	global_load_dwordx4 v[78:81], v[40:41], off offset:128
	global_load_dwordx4 v[82:85], v[40:41], off offset:256
	global_load_dwordx4 v[86:89], v[48:49], off offset:128
	global_load_dwordx4 v[90:93], v[48:49], off offset:256
	global_load_dwordx4 v[94:97], v[36:37], off offset:128
	global_load_dwordx4 v[98:101], v[38:39], off offset:128
	global_load_dwordx4 v[102:105], v[46:47], off offset:128
	global_load_dwordx4 v[106:109], v[46:47], off offset:256
	global_load_dwordx4 v[110:113], v[38:39], off offset:256
	global_load_dwordx4 v[114:117], v[36:37], off offset:256
	global_load_dwordx4 v[118:121], v[34:35], off offset:256
	v_and_b32_e32 v53, 31, v52
	v_ashrrev_i32_e32 v55, 1, v52
	s_movk_i32 s0, 0xffc0
	v_and_or_b32 v55, v55, s0, v53
	v_add_u32_e32 v57, 0x9000, v54
	s_waitcnt vmcnt(23)
	ds_write_b128 v54, v[2:5]
	s_waitcnt vmcnt(20)
	ds_write_b128 v54, v[14:17] offset:18432
	s_waitcnt vmcnt(19)
	ds_write_b128 v54, v[18:21] offset:23040
	s_waitcnt vmcnt(18)
	ds_write_b128 v54, v[22:25] offset:27648
	s_waitcnt vmcnt(17)
	ds_write_b128 v54, v[26:29] offset:32256
	ds_write_b128 v54, v[6:9] offset:4608
	ds_write_b128 v54, v[10:13] offset:9216
	s_waitcnt vmcnt(16)
	ds_write_b128 v54, v[30:33] offset:13824
	s_waitcnt lgkmcnt(0)
	s_barrier
	ds_read_b128 v[2:5], v0 offset:18432
	v_mul_lo_u32 v6, v55, s4
	v_add3_u32 v56, v6, v122, v232
	ds_read_b128 v[6:9], v56
	ds_read_b128 v[122:125], v56 offset:32
	ds_read_b128 v[126:129], v0 offset:18464
	s_waitcnt lgkmcnt(2)
	v_mfma_f32_32x32x16_bf16 v[18:33], v[2:5], v[6:9], 0
	ds_read_b128 v[6:9], v56 offset:4608
	ds_read_b128 v[130:133], v56 offset:4640
	s_waitcnt lgkmcnt(1)
	v_mfma_f32_32x32x16_bf16 v[2:17], v[2:5], v[6:9], 0
	v_mfma_f32_32x32x16_bf16 v[18:33], v[126:129], v[122:125], v[18:33]
	s_waitcnt lgkmcnt(0)
	v_mfma_f32_32x32x16_bf16 v[2:17], v[126:129], v[130:133], v[2:17]
	ds_read_b128 v[122:125], v0 offset:18496
	ds_read_b128 v[126:129], v56 offset:64
	ds_read_b128 v[130:133], v56 offset:96
	ds_read_b128 v[134:137], v0 offset:18528
	s_waitcnt lgkmcnt(2)
	v_mfma_f32_32x32x16_bf16 v[18:33], v[122:125], v[126:129], v[18:33]
	ds_read_b128 v[126:129], v56 offset:4672
	ds_read_b128 v[138:141], v56 offset:4704
	s_waitcnt lgkmcnt(1)
	v_mfma_f32_32x32x16_bf16 v[2:17], v[122:125], v[126:129], v[2:17]
	global_load_dwordx4 v[122:125], v[36:37], off offset:384
	global_load_dwordx4 v[126:129], v[38:39], off offset:384
	global_load_dwordx4 v[142:145], v[34:35], off offset:384
	global_load_dwordx4 v[146:149], v[48:49], off offset:384
	v_mfma_f32_32x32x16_bf16 v[18:33], v[134:137], v[130:133], v[18:33]
	global_load_dwordx4 v[130:133], v[46:47], off offset:384
	global_load_dwordx4 v[150:153], v[40:41], off offset:384
	global_load_dwordx4 v[154:157], v[42:43], off offset:384
	global_load_dwordx4 v[158:161], v[44:45], off offset:384
	s_waitcnt vmcnt(23)
	ds_write_b128 v54, v[58:61] offset:36864
	s_waitcnt vmcnt(14)
	ds_write_b128 v54, v[94:97] offset:41472
	s_waitcnt vmcnt(13)
	ds_write_b128 v54, v[98:101] offset:46080
	s_waitcnt vmcnt(12)
	ds_write_b128 v54, v[102:105] offset:50688
	ds_write_b128 v54, v[86:89] offset:55296
	ds_write_b128 v54, v[78:81] offset:59904
	ds_write_b128 v54, v[62:65] offset:64512
	ds_write_b128 v57, v[66:69] offset:32256
	s_waitcnt lgkmcnt(0)
	s_barrier
	ds_read_b128 v[58:61], v0 offset:55296
	ds_read_b128 v[62:65], v56 offset:36864
	ds_read_b128 v[66:69], v56 offset:36896
	ds_read_b128 v[78:81], v0 offset:55328
	v_mfma_f32_32x32x16_bf16 v[2:17], v[134:137], v[138:141], v[2:17]
	s_waitcnt lgkmcnt(2)
	v_mfma_f32_32x32x16_bf16 v[18:33], v[58:61], v[62:65], v[18:33]
	ds_read_b128 v[62:65], v56 offset:41472
	ds_read_b128 v[86:89], v56 offset:41504
	s_waitcnt lgkmcnt(1)
	v_mfma_f32_32x32x16_bf16 v[2:17], v[58:61], v[62:65], v[2:17]
	v_mfma_f32_32x32x16_bf16 v[18:33], v[78:81], v[66:69], v[18:33]
	s_waitcnt lgkmcnt(0)
	v_mfma_f32_32x32x16_bf16 v[2:17], v[78:81], v[86:89], v[2:17]
	ds_read_b128 v[58:61], v0 offset:55360
	ds_read_b128 v[62:65], v56 offset:36928
	ds_read_b128 v[66:69], v56 offset:36960
	ds_read_b128 v[78:81], v0 offset:55392
	s_waitcnt lgkmcnt(2)
	v_mfma_f32_32x32x16_bf16 v[18:33], v[58:61], v[62:65], v[18:33]
	ds_read_b128 v[62:65], v56 offset:41536
	ds_read_b128 v[86:89], v56 offset:41568
	s_waitcnt lgkmcnt(1)
	v_mfma_f32_32x32x16_bf16 v[2:17], v[58:61], v[62:65], v[2:17]
	v_add_u32_e32 v58, 0x10e00, v54
	v_mfma_f32_32x32x16_bf16 v[18:33], v[78:81], v[66:69], v[18:33]
	global_load_dwordx4 v[60:63], v[36:37], off offset:512
	global_load_dwordx4 v[64:67], v[38:39], off offset:512
	global_load_dwordx4 v[94:97], v[34:35], off offset:512
	global_load_dwordx4 v[98:101], v[48:49], off offset:512
	global_load_dwordx4 v[102:105], v[46:47], off offset:512
	global_load_dwordx4 v[134:137], v[40:41], off offset:512
	global_load_dwordx4 v[138:141], v[42:43], off offset:512
	global_load_dwordx4 v[164:167], v[44:45], off offset:512
	s_waitcnt vmcnt(16)
	ds_write_b128 v54, v[118:121]
	ds_write_b128 v54, v[114:117] offset:4608
	ds_write_b128 v54, v[110:113] offset:9216
	ds_write_b128 v54, v[106:109] offset:13824
	ds_write_b128 v54, v[90:93] offset:18432
	ds_write_b128 v54, v[82:85] offset:23040
	ds_write_b128 v54, v[74:77] offset:27648
	ds_write_b128 v54, v[70:73] offset:32256
	s_waitcnt lgkmcnt(0)
	s_barrier
	v_mfma_f32_32x32x16_bf16 v[2:17], v[78:81], v[86:89], v[2:17]
	ds_read_b128 v[68:71], v0 offset:18432
	ds_read_b128 v[72:75], v56
	ds_read_b128 v[76:79], v56 offset:32
	ds_read_b128 v[80:83], v0 offset:18464
	s_waitcnt lgkmcnt(2)
	v_mfma_f32_32x32x16_bf16 v[18:33], v[68:71], v[72:75], v[18:33]
	ds_read_b128 v[72:75], v56 offset:4608
	ds_read_b128 v[84:87], v56 offset:4640
	s_waitcnt lgkmcnt(1)
	v_mfma_f32_32x32x16_bf16 v[2:17], v[68:71], v[72:75], v[2:17]
	v_mfma_f32_32x32x16_bf16 v[18:33], v[80:83], v[76:79], v[18:33]
	s_waitcnt lgkmcnt(0)
	v_mfma_f32_32x32x16_bf16 v[2:17], v[80:83], v[84:87], v[2:17]
	ds_read_b128 v[68:71], v0 offset:18496
	ds_read_b128 v[72:75], v56 offset:64
	ds_read_b128 v[76:79], v56 offset:96
	ds_read_b128 v[80:83], v0 offset:18528
	s_waitcnt lgkmcnt(2)
	v_mfma_f32_32x32x16_bf16 v[18:33], v[68:71], v[72:75], v[18:33]
	ds_read_b128 v[72:75], v56 offset:4672
	ds_read_b128 v[84:87], v56 offset:4704
	s_waitcnt lgkmcnt(1)
	v_mfma_f32_32x32x16_bf16 v[2:17], v[68:71], v[72:75], v[2:17]
	v_mfma_f32_32x32x16_bf16 v[18:33], v[80:83], v[76:79], v[18:33]
	global_load_dwordx4 v[68:71], v[36:37], off offset:640
	global_load_dwordx4 v[72:75], v[38:39], off offset:640
	global_load_dwordx4 v[76:79], v[34:35], off offset:640
	global_load_dwordx4 v[88:91], v[48:49], off offset:640
	global_load_dwordx4 v[106:109], v[46:47], off offset:640
	global_load_dwordx4 v[110:113], v[40:41], off offset:640
	global_load_dwordx4 v[114:117], v[42:43], off offset:640
	global_load_dwordx4 v[118:121], v[44:45], off offset:640
	s_waitcnt vmcnt(21)
	ds_write_b128 v54, v[142:145] offset:36864
	ds_write_b128 v54, v[122:125] offset:41472
	ds_write_b128 v54, v[126:129] offset:46080
	s_waitcnt vmcnt(19)
	ds_write_b128 v54, v[130:133] offset:50688
	ds_write_b128 v54, v[146:149] offset:55296
	s_waitcnt vmcnt(18)
	ds_write_b128 v54, v[150:153] offset:59904
	s_waitcnt vmcnt(17)
	ds_write_b128 v54, v[154:157] offset:64512
	s_waitcnt vmcnt(16)
	ds_write_b128 v58, v[158:161]
	s_waitcnt lgkmcnt(0)
	s_barrier
	v_mfma_f32_32x32x16_bf16 v[2:17], v[80:83], v[84:87], v[2:17]
	ds_read_b128 v[80:83], v0 offset:55296
	ds_read_b128 v[84:87], v56 offset:36864
	ds_read_b128 v[122:125], v56 offset:36896
	ds_read_b128 v[126:129], v0 offset:55328
	s_waitcnt lgkmcnt(2)
	v_mfma_f32_32x32x16_bf16 v[18:33], v[80:83], v[84:87], v[18:33]
	ds_read_b128 v[84:87], v56 offset:41472
	ds_read_b128 v[130:133], v56 offset:41504
	s_waitcnt lgkmcnt(1)
	v_mfma_f32_32x32x16_bf16 v[2:17], v[80:83], v[84:87], v[2:17]
	v_mfma_f32_32x32x16_bf16 v[18:33], v[126:129], v[122:125], v[18:33]
	s_waitcnt lgkmcnt(0)
	v_mfma_f32_32x32x16_bf16 v[2:17], v[126:129], v[130:133], v[2:17]
	ds_read_b128 v[80:83], v0 offset:55360
	ds_read_b128 v[84:87], v56 offset:36928
	ds_read_b128 v[122:125], v56 offset:36960
	ds_read_b128 v[126:129], v0 offset:55392
	s_waitcnt lgkmcnt(2)
	v_mfma_f32_32x32x16_bf16 v[18:33], v[80:83], v[84:87], v[18:33]
	ds_read_b128 v[84:87], v56 offset:41536
	ds_read_b128 v[130:133], v56 offset:41568
	s_waitcnt lgkmcnt(1)
	v_mfma_f32_32x32x16_bf16 v[2:17], v[80:83], v[84:87], v[2:17]
	v_mfma_f32_32x32x16_bf16 v[18:33], v[126:129], v[122:125], v[18:33]
	global_load_dwordx4 v[80:83], v[36:37], off offset:768
	global_load_dwordx4 v[84:87], v[38:39], off offset:768
	global_load_dwordx4 v[122:125], v[34:35], off offset:768
	global_load_dwordx4 v[142:145], v[48:49], off offset:768
	global_load_dwordx4 v[146:149], v[46:47], off offset:768
	global_load_dwordx4 v[150:153], v[40:41], off offset:768
	global_load_dwordx4 v[154:157], v[42:43], off offset:768
	global_load_dwordx4 v[158:161], v[44:45], off offset:768
	s_waitcnt vmcnt(21)
	ds_write_b128 v54, v[94:97]
	ds_write_b128 v54, v[60:63] offset:4608
	ds_write_b128 v54, v[64:67] offset:9216
	s_waitcnt vmcnt(19)
	ds_write_b128 v54, v[102:105] offset:13824
	ds_write_b128 v54, v[98:101] offset:18432
	s_waitcnt vmcnt(18)
	ds_write_b128 v54, v[134:137] offset:23040
	s_waitcnt vmcnt(17)
	ds_write_b128 v54, v[138:141] offset:27648
	s_waitcnt vmcnt(16)
	ds_write_b128 v54, v[164:167] offset:32256
	s_waitcnt lgkmcnt(0)
	s_barrier
	ds_read_b128 v[60:63], v0 offset:18432
	ds_read_b128 v[64:67], v56
	ds_read_b128 v[92:95], v56 offset:32
	ds_read_b128 v[96:99], v0 offset:18464
	v_mfma_f32_32x32x16_bf16 v[2:17], v[126:129], v[130:133], v[2:17]
	s_waitcnt lgkmcnt(2)
	v_mfma_f32_32x32x16_bf16 v[18:33], v[60:63], v[64:67], v[18:33]
	ds_read_b128 v[64:67], v56 offset:4608
	ds_read_b128 v[100:103], v56 offset:4640
	s_waitcnt lgkmcnt(1)
	v_mfma_f32_32x32x16_bf16 v[2:17], v[60:63], v[64:67], v[2:17]
	v_mfma_f32_32x32x16_bf16 v[18:33], v[96:99], v[92:95], v[18:33]
	s_waitcnt lgkmcnt(0)
	v_mfma_f32_32x32x16_bf16 v[2:17], v[96:99], v[100:103], v[2:17]
	ds_read_b128 v[60:63], v0 offset:18496
	ds_read_b128 v[64:67], v56 offset:64
	ds_read_b128 v[92:95], v56 offset:96
	ds_read_b128 v[96:99], v0 offset:18528
	s_waitcnt lgkmcnt(2)
	v_mfma_f32_32x32x16_bf16 v[18:33], v[60:63], v[64:67], v[18:33]
	ds_read_b128 v[64:67], v56 offset:4672
	ds_read_b128 v[100:103], v56 offset:4704
	s_waitcnt lgkmcnt(1)
	v_mfma_f32_32x32x16_bf16 v[2:17], v[60:63], v[64:67], v[2:17]
	v_mfma_f32_32x32x16_bf16 v[18:33], v[96:99], v[92:95], v[18:33]
	global_load_dwordx4 v[60:63], v[36:37], off offset:896
	global_load_dwordx4 v[64:67], v[38:39], off offset:896
	global_load_dwordx4 v[92:95], v[34:35], off offset:896
	global_load_dwordx4 v[126:129], v[48:49], off offset:896
	global_load_dwordx4 v[130:133], v[46:47], off offset:896
	global_load_dwordx4 v[134:137], v[40:41], off offset:896
	global_load_dwordx4 v[138:141], v[42:43], off offset:896
	global_load_dwordx4 v[164:167], v[44:45], off offset:896
	s_waitcnt vmcnt(21)
	ds_write_b128 v54, v[76:79] offset:36864
	ds_write_b128 v54, v[68:71] offset:41472
	ds_write_b128 v54, v[72:75] offset:46080
	s_waitcnt vmcnt(19)
	ds_write_b128 v54, v[106:109] offset:50688
	ds_write_b128 v54, v[88:91] offset:55296
	s_waitcnt vmcnt(18)
	ds_write_b128 v54, v[110:113] offset:59904
	s_waitcnt vmcnt(17)
	ds_write_b128 v54, v[114:117] offset:64512
	s_waitcnt vmcnt(16)
	ds_write_b128 v57, v[118:121] offset:32256
	s_waitcnt lgkmcnt(0)
	s_barrier
	ds_read_b128 v[68:71], v0 offset:55296
	ds_read_b128 v[72:75], v56 offset:36864
	ds_read_b128 v[76:79], v56 offset:36896
	ds_read_b128 v[88:91], v0 offset:55328
	v_mfma_f32_32x32x16_bf16 v[2:17], v[96:99], v[100:103], v[2:17]
	s_waitcnt lgkmcnt(2)
	v_mfma_f32_32x32x16_bf16 v[18:33], v[68:71], v[72:75], v[18:33]
	ds_read_b128 v[72:75], v56 offset:41472
	ds_read_b128 v[96:99], v56 offset:41504
	s_waitcnt lgkmcnt(1)
	v_mfma_f32_32x32x16_bf16 v[2:17], v[68:71], v[72:75], v[2:17]
	v_mfma_f32_32x32x16_bf16 v[18:33], v[88:91], v[76:79], v[18:33]
	s_waitcnt lgkmcnt(0)
	v_mfma_f32_32x32x16_bf16 v[2:17], v[88:91], v[96:99], v[2:17]
	ds_read_b128 v[68:71], v0 offset:55360
	ds_read_b128 v[72:75], v56 offset:36928
	ds_read_b128 v[76:79], v56 offset:36960
	ds_read_b128 v[88:91], v0 offset:55392
	s_waitcnt lgkmcnt(2)
	v_mfma_f32_32x32x16_bf16 v[18:33], v[68:71], v[72:75], v[18:33]
	ds_read_b128 v[72:75], v56 offset:41536
	ds_read_b128 v[96:99], v56 offset:41568
	s_waitcnt lgkmcnt(1)
	v_mfma_f32_32x32x16_bf16 v[2:17], v[68:71], v[72:75], v[2:17]
	v_mfma_f32_32x32x16_bf16 v[18:33], v[88:91], v[76:79], v[18:33]
	global_load_dwordx4 v[68:71], v[36:37], off offset:1024
	global_load_dwordx4 v[72:75], v[38:39], off offset:1024
	global_load_dwordx4 v[76:79], v[34:35], off offset:1024
	global_load_dwordx4 v[100:103], v[48:49], off offset:1024
	global_load_dwordx4 v[104:107], v[46:47], off offset:1024
	global_load_dwordx4 v[108:111], v[40:41], off offset:1024
	global_load_dwordx4 v[112:115], v[42:43], off offset:1024
	global_load_dwordx4 v[116:119], v[44:45], off offset:1024
	s_waitcnt vmcnt(21)
	ds_write_b128 v54, v[122:125]
	ds_write_b128 v54, v[80:83] offset:4608
	ds_write_b128 v54, v[84:87] offset:9216
	s_waitcnt vmcnt(19)
	ds_write_b128 v54, v[146:149] offset:13824
	ds_write_b128 v54, v[142:145] offset:18432
	s_waitcnt vmcnt(18)
	ds_write_b128 v54, v[150:153] offset:23040
	s_waitcnt vmcnt(17)
	ds_write_b128 v54, v[154:157] offset:27648
	s_waitcnt vmcnt(16)
	ds_write_b128 v54, v[158:161] offset:32256
	s_waitcnt lgkmcnt(0)
	s_barrier
	v_mfma_f32_32x32x16_bf16 v[2:17], v[88:91], v[96:99], v[2:17]
	ds_read_b128 v[80:83], v0 offset:18432
	ds_read_b128 v[84:87], v56
	ds_read_b128 v[88:91], v56 offset:32
	ds_read_b128 v[96:99], v0 offset:18464
	s_waitcnt lgkmcnt(2)
	v_mfma_f32_32x32x16_bf16 v[18:33], v[80:83], v[84:87], v[18:33]
	ds_read_b128 v[84:87], v56 offset:4608
	ds_read_b128 v[120:123], v56 offset:4640
	s_waitcnt lgkmcnt(1)
	v_mfma_f32_32x32x16_bf16 v[2:17], v[80:83], v[84:87], v[2:17]
	v_mfma_f32_32x32x16_bf16 v[18:33], v[96:99], v[88:91], v[18:33]
	s_waitcnt lgkmcnt(0)
	v_mfma_f32_32x32x16_bf16 v[2:17], v[96:99], v[120:123], v[2:17]
	ds_read_b128 v[80:83], v0 offset:18496
	ds_read_b128 v[84:87], v56 offset:64
	ds_read_b128 v[88:91], v56 offset:96
	ds_read_b128 v[96:99], v0 offset:18528
	s_waitcnt lgkmcnt(2)
	v_mfma_f32_32x32x16_bf16 v[18:33], v[80:83], v[84:87], v[18:33]
	ds_read_b128 v[84:87], v56 offset:4672
	ds_read_b128 v[120:123], v56 offset:4704
	s_waitcnt lgkmcnt(1)
	v_mfma_f32_32x32x16_bf16 v[2:17], v[80:83], v[84:87], v[2:17]
	v_mfma_f32_32x32x16_bf16 v[18:33], v[96:99], v[88:91], v[18:33]
	global_load_dwordx4 v[80:83], v[36:37], off offset:1152
	global_load_dwordx4 v[84:87], v[38:39], off offset:1152
	global_load_dwordx4 v[88:91], v[34:35], off offset:1152
	global_load_dwordx4 v[142:145], v[48:49], off offset:1152
	global_load_dwordx4 v[146:149], v[46:47], off offset:1152
	global_load_dwordx4 v[150:153], v[40:41], off offset:1152
	global_load_dwordx4 v[154:157], v[42:43], off offset:1152
	global_load_dwordx4 v[158:161], v[44:45], off offset:1152
	s_waitcnt vmcnt(21)
	ds_write_b128 v54, v[92:95] offset:36864
	ds_write_b128 v54, v[60:63] offset:41472
	ds_write_b128 v54, v[64:67] offset:46080
	s_waitcnt vmcnt(19)
	ds_write_b128 v54, v[130:133] offset:50688
	ds_write_b128 v54, v[126:129] offset:55296
	s_waitcnt vmcnt(18)
	ds_write_b128 v54, v[134:137] offset:59904
	s_waitcnt vmcnt(17)
	ds_write_b128 v54, v[138:141] offset:64512
	s_waitcnt vmcnt(16)
	ds_write_b128 v57, v[164:167] offset:32256
	s_waitcnt lgkmcnt(0)
	s_barrier
	v_mfma_f32_32x32x16_bf16 v[2:17], v[96:99], v[120:123], v[2:17]
	ds_read_b128 v[60:63], v0 offset:55296
	ds_read_b128 v[64:67], v56 offset:36864
	ds_read_b128 v[92:95], v56 offset:36896
	ds_read_b128 v[96:99], v0 offset:55328
	s_waitcnt lgkmcnt(2)
	v_mfma_f32_32x32x16_bf16 v[18:33], v[60:63], v[64:67], v[18:33]
	ds_read_b128 v[64:67], v56 offset:41472
	ds_read_b128 v[120:123], v56 offset:41504
	s_waitcnt lgkmcnt(1)
	v_mfma_f32_32x32x16_bf16 v[2:17], v[60:63], v[64:67], v[2:17]
	v_mfma_f32_32x32x16_bf16 v[18:33], v[96:99], v[92:95], v[18:33]
	s_waitcnt lgkmcnt(0)
	v_mfma_f32_32x32x16_bf16 v[2:17], v[96:99], v[120:123], v[2:17]
	ds_read_b128 v[60:63], v0 offset:55360
	ds_read_b128 v[64:67], v56 offset:36928
	ds_read_b128 v[92:95], v56 offset:36960
	ds_read_b128 v[96:99], v0 offset:55392
	s_waitcnt lgkmcnt(2)
	v_mfma_f32_32x32x16_bf16 v[18:33], v[60:63], v[64:67], v[18:33]
	ds_read_b128 v[64:67], v56 offset:41536
	ds_read_b128 v[120:123], v56 offset:41568
	s_waitcnt lgkmcnt(1)
	v_mfma_f32_32x32x16_bf16 v[2:17], v[60:63], v[64:67], v[2:17]
	v_mfma_f32_32x32x16_bf16 v[18:33], v[96:99], v[92:95], v[18:33]
	global_load_dwordx4 v[60:63], v[36:37], off offset:1280
	global_load_dwordx4 v[64:67], v[38:39], off offset:1280
	global_load_dwordx4 v[92:95], v[34:35], off offset:1280
	global_load_dwordx4 v[124:127], v[48:49], off offset:1280
	global_load_dwordx4 v[128:131], v[46:47], off offset:1280
	global_load_dwordx4 v[132:135], v[40:41], off offset:1280
	global_load_dwordx4 v[136:139], v[42:43], off offset:1280
	global_load_dwordx4 v[164:167], v[44:45], off offset:1280
	s_waitcnt vmcnt(21)
	ds_write_b128 v54, v[76:79]
	ds_write_b128 v54, v[68:71] offset:4608
	ds_write_b128 v54, v[72:75] offset:9216
	s_waitcnt vmcnt(19)
	ds_write_b128 v54, v[104:107] offset:13824
	ds_write_b128 v54, v[100:103] offset:18432
	s_waitcnt vmcnt(18)
	ds_write_b128 v54, v[108:111] offset:23040
	s_waitcnt vmcnt(17)
	ds_write_b128 v54, v[112:115] offset:27648
	s_waitcnt vmcnt(16)
	ds_write_b128 v54, v[116:119] offset:32256
	s_waitcnt lgkmcnt(0)
	s_barrier
	v_mfma_f32_32x32x16_bf16 v[2:17], v[96:99], v[120:123], v[2:17]
	ds_read_b128 v[68:71], v0 offset:18432
	ds_read_b128 v[72:75], v56
	ds_read_b128 v[76:79], v56 offset:32
	ds_read_b128 v[96:99], v0 offset:18464
	s_waitcnt lgkmcnt(2)
	v_mfma_f32_32x32x16_bf16 v[18:33], v[68:71], v[72:75], v[18:33]
	ds_read_b128 v[72:75], v56 offset:4608
	ds_read_b128 v[100:103], v56 offset:4640
	s_waitcnt lgkmcnt(1)
	v_mfma_f32_32x32x16_bf16 v[2:17], v[68:71], v[72:75], v[2:17]
	v_mfma_f32_32x32x16_bf16 v[18:33], v[96:99], v[76:79], v[18:33]
	s_waitcnt lgkmcnt(0)
	v_mfma_f32_32x32x16_bf16 v[2:17], v[96:99], v[100:103], v[2:17]
	ds_read_b128 v[68:71], v0 offset:18496
	ds_read_b128 v[72:75], v56 offset:64
	ds_read_b128 v[76:79], v56 offset:96
	ds_read_b128 v[96:99], v0 offset:18528
	s_waitcnt lgkmcnt(2)
	v_mfma_f32_32x32x16_bf16 v[18:33], v[68:71], v[72:75], v[18:33]
	ds_read_b128 v[72:75], v56 offset:4672
	ds_read_b128 v[100:103], v56 offset:4704
	s_waitcnt lgkmcnt(1)
	v_mfma_f32_32x32x16_bf16 v[2:17], v[68:71], v[72:75], v[2:17]
	v_mfma_f32_32x32x16_bf16 v[18:33], v[96:99], v[76:79], v[18:33]
	global_load_dwordx4 v[68:71], v[36:37], off offset:1408
	global_load_dwordx4 v[72:75], v[38:39], off offset:1408
	global_load_dwordx4 v[76:79], v[34:35], off offset:1408
	global_load_dwordx4 v[104:107], v[48:49], off offset:1408
	global_load_dwordx4 v[108:111], v[46:47], off offset:1408
	global_load_dwordx4 v[112:115], v[40:41], off offset:1408
	global_load_dwordx4 v[116:119], v[42:43], off offset:1408
	global_load_dwordx4 v[120:123], v[44:45], off offset:1408
	s_waitcnt vmcnt(21)
	ds_write_b128 v54, v[88:91] offset:36864
	ds_write_b128 v54, v[80:83] offset:41472
	ds_write_b128 v54, v[84:87] offset:46080
	s_waitcnt vmcnt(19)
	ds_write_b128 v54, v[146:149] offset:50688
	ds_write_b128 v54, v[142:145] offset:55296
	s_waitcnt vmcnt(18)
	ds_write_b128 v54, v[150:153] offset:59904
	s_waitcnt vmcnt(17)
	ds_write_b128 v54, v[154:157] offset:64512
	s_waitcnt vmcnt(16)
	ds_write_b128 v58, v[158:161]
	s_waitcnt lgkmcnt(0)
	s_barrier
	v_mfma_f32_32x32x16_bf16 v[2:17], v[96:99], v[100:103], v[2:17]
	ds_read_b128 v[80:83], v0 offset:55296
	ds_read_b128 v[84:87], v56 offset:36864
	ds_read_b128 v[88:91], v56 offset:36896
	ds_read_b128 v[96:99], v0 offset:55328
	s_waitcnt lgkmcnt(2)
	v_mfma_f32_32x32x16_bf16 v[18:33], v[80:83], v[84:87], v[18:33]
	ds_read_b128 v[84:87], v56 offset:41472
	ds_read_b128 v[100:103], v56 offset:41504
	s_waitcnt lgkmcnt(1)
	v_mfma_f32_32x32x16_bf16 v[2:17], v[80:83], v[84:87], v[2:17]
	v_mfma_f32_32x32x16_bf16 v[18:33], v[96:99], v[88:91], v[18:33]
	s_waitcnt lgkmcnt(0)
	v_mfma_f32_32x32x16_bf16 v[2:17], v[96:99], v[100:103], v[2:17]
	ds_read_b128 v[80:83], v0 offset:55360
	ds_read_b128 v[84:87], v56 offset:36928
	ds_read_b128 v[88:91], v56 offset:36960
	ds_read_b128 v[96:99], v0 offset:55392
	s_waitcnt lgkmcnt(2)
	v_mfma_f32_32x32x16_bf16 v[18:33], v[80:83], v[84:87], v[18:33]
	ds_read_b128 v[84:87], v56 offset:41536
	ds_read_b128 v[100:103], v56 offset:41568
	s_waitcnt lgkmcnt(1)
	v_mfma_f32_32x32x16_bf16 v[2:17], v[80:83], v[84:87], v[2:17]
	v_mfma_f32_32x32x16_bf16 v[18:33], v[96:99], v[88:91], v[18:33]
	global_load_dwordx4 v[80:83], v[36:37], off offset:1536
	global_load_dwordx4 v[84:87], v[38:39], off offset:1536
	global_load_dwordx4 v[88:91], v[34:35], off offset:1536
	global_load_dwordx4 v[140:143], v[48:49], off offset:1536
	global_load_dwordx4 v[144:147], v[46:47], off offset:1536
	global_load_dwordx4 v[148:151], v[40:41], off offset:1536
	global_load_dwordx4 v[152:155], v[42:43], off offset:1536
	global_load_dwordx4 v[156:159], v[44:45], off offset:1536
	s_waitcnt vmcnt(21)
	ds_write_b128 v54, v[92:95]
	ds_write_b128 v54, v[60:63] offset:4608
	ds_write_b128 v54, v[64:67] offset:9216
	s_waitcnt vmcnt(19)
	ds_write_b128 v54, v[128:131] offset:13824
	ds_write_b128 v54, v[124:127] offset:18432
	s_waitcnt vmcnt(18)
	ds_write_b128 v54, v[132:135] offset:23040
	s_waitcnt vmcnt(17)
	ds_write_b128 v54, v[136:139] offset:27648
	s_waitcnt vmcnt(16)
	ds_write_b128 v54, v[164:167] offset:32256
	s_waitcnt lgkmcnt(0)
	s_barrier
	v_mfma_f32_32x32x16_bf16 v[2:17], v[96:99], v[100:103], v[2:17]
	ds_read_b128 v[60:63], v0 offset:18432
	ds_read_b128 v[64:67], v56
	ds_read_b128 v[92:95], v56 offset:32
	ds_read_b128 v[96:99], v0 offset:18464
	s_waitcnt lgkmcnt(2)
	v_mfma_f32_32x32x16_bf16 v[18:33], v[60:63], v[64:67], v[18:33]
	ds_read_b128 v[64:67], v56 offset:4608
	ds_read_b128 v[100:103], v56 offset:4640
	s_waitcnt lgkmcnt(1)
	v_mfma_f32_32x32x16_bf16 v[2:17], v[60:63], v[64:67], v[2:17]
	v_mfma_f32_32x32x16_bf16 v[18:33], v[96:99], v[92:95], v[18:33]
	s_waitcnt lgkmcnt(0)
	v_mfma_f32_32x32x16_bf16 v[2:17], v[96:99], v[100:103], v[2:17]
	ds_read_b128 v[60:63], v0 offset:18496
	ds_read_b128 v[64:67], v56 offset:64
	ds_read_b128 v[92:95], v56 offset:96
	ds_read_b128 v[96:99], v0 offset:18528
	s_waitcnt lgkmcnt(2)
	v_mfma_f32_32x32x16_bf16 v[18:33], v[60:63], v[64:67], v[18:33]
	ds_read_b128 v[64:67], v56 offset:4672
	ds_read_b128 v[100:103], v56 offset:4704
	s_waitcnt lgkmcnt(1)
	v_mfma_f32_32x32x16_bf16 v[2:17], v[60:63], v[64:67], v[2:17]
	v_mfma_f32_32x32x16_bf16 v[18:33], v[96:99], v[92:95], v[18:33]
	global_load_dwordx4 v[60:63], v[36:37], off offset:1664
	global_load_dwordx4 v[64:67], v[38:39], off offset:1664
	global_load_dwordx4 v[92:95], v[34:35], off offset:1664
	global_load_dwordx4 v[124:127], v[48:49], off offset:1664
	global_load_dwordx4 v[128:131], v[46:47], off offset:1664
	global_load_dwordx4 v[132:135], v[40:41], off offset:1664
	global_load_dwordx4 v[136:139], v[42:43], off offset:1664
	global_load_dwordx4 v[164:167], v[44:45], off offset:1664
	s_waitcnt vmcnt(21)
	ds_write_b128 v54, v[76:79] offset:36864
	ds_write_b128 v54, v[68:71] offset:41472
	ds_write_b128 v54, v[72:75] offset:46080
	s_waitcnt vmcnt(19)
	ds_write_b128 v54, v[108:111] offset:50688
	ds_write_b128 v54, v[104:107] offset:55296
	s_waitcnt vmcnt(18)
	ds_write_b128 v54, v[112:115] offset:59904
	s_waitcnt vmcnt(17)
	ds_write_b128 v54, v[116:119] offset:64512
	s_waitcnt vmcnt(16)
	ds_write_b128 v57, v[120:123] offset:32256
	s_waitcnt lgkmcnt(0)
	s_barrier
	v_mfma_f32_32x32x16_bf16 v[2:17], v[96:99], v[100:103], v[2:17]
	ds_read_b128 v[68:71], v0 offset:55296
	ds_read_b128 v[72:75], v56 offset:36864
	ds_read_b128 v[76:79], v56 offset:36896
	ds_read_b128 v[96:99], v0 offset:55328
	s_waitcnt lgkmcnt(2)
	v_mfma_f32_32x32x16_bf16 v[18:33], v[68:71], v[72:75], v[18:33]
	ds_read_b128 v[72:75], v56 offset:41472
	ds_read_b128 v[100:103], v56 offset:41504
	s_waitcnt lgkmcnt(1)
	v_mfma_f32_32x32x16_bf16 v[2:17], v[68:71], v[72:75], v[2:17]
	v_mfma_f32_32x32x16_bf16 v[18:33], v[96:99], v[76:79], v[18:33]
	s_waitcnt lgkmcnt(0)
	v_mfma_f32_32x32x16_bf16 v[2:17], v[96:99], v[100:103], v[2:17]
	ds_read_b128 v[68:71], v0 offset:55360
	ds_read_b128 v[72:75], v56 offset:36928
	ds_read_b128 v[76:79], v56 offset:36960
	ds_read_b128 v[96:99], v0 offset:55392
	s_waitcnt lgkmcnt(2)
	v_mfma_f32_32x32x16_bf16 v[18:33], v[68:71], v[72:75], v[18:33]
	ds_read_b128 v[72:75], v56 offset:41536
	ds_read_b128 v[100:103], v56 offset:41568
	s_waitcnt lgkmcnt(1)
	v_mfma_f32_32x32x16_bf16 v[2:17], v[68:71], v[72:75], v[2:17]
	v_mfma_f32_32x32x16_bf16 v[18:33], v[96:99], v[76:79], v[18:33]
	global_load_dwordx4 v[68:71], v[36:37], off offset:1792
	global_load_dwordx4 v[72:75], v[38:39], off offset:1792
	global_load_dwordx4 v[76:79], v[34:35], off offset:1792
	global_load_dwordx4 v[104:107], v[48:49], off offset:1792
	global_load_dwordx4 v[108:111], v[46:47], off offset:1792
	global_load_dwordx4 v[112:115], v[40:41], off offset:1792
	global_load_dwordx4 v[116:119], v[42:43], off offset:1792
	global_load_dwordx4 v[120:123], v[44:45], off offset:1792
	s_waitcnt vmcnt(21)
	ds_write_b128 v54, v[88:91]
	ds_write_b128 v54, v[80:83] offset:4608
	ds_write_b128 v54, v[84:87] offset:9216
	s_waitcnt vmcnt(19)
	ds_write_b128 v54, v[144:147] offset:13824
	ds_write_b128 v54, v[140:143] offset:18432
	s_waitcnt vmcnt(18)
	ds_write_b128 v54, v[148:151] offset:23040
	s_waitcnt vmcnt(17)
	ds_write_b128 v54, v[152:155] offset:27648
	s_waitcnt vmcnt(16)
	ds_write_b128 v54, v[156:159] offset:32256
	s_waitcnt lgkmcnt(0)
	s_barrier
	v_mfma_f32_32x32x16_bf16 v[2:17], v[96:99], v[100:103], v[2:17]
	ds_read_b128 v[80:83], v0 offset:18432
	ds_read_b128 v[84:87], v56
	ds_read_b128 v[88:91], v56 offset:32
	ds_read_b128 v[96:99], v0 offset:18464
	s_waitcnt lgkmcnt(2)
	v_mfma_f32_32x32x16_bf16 v[18:33], v[80:83], v[84:87], v[18:33]
	ds_read_b128 v[84:87], v56 offset:4608
	ds_read_b128 v[100:103], v56 offset:4640
	s_waitcnt lgkmcnt(1)
	v_mfma_f32_32x32x16_bf16 v[2:17], v[80:83], v[84:87], v[2:17]
	v_mfma_f32_32x32x16_bf16 v[18:33], v[96:99], v[88:91], v[18:33]
	s_waitcnt lgkmcnt(0)
	v_mfma_f32_32x32x16_bf16 v[2:17], v[96:99], v[100:103], v[2:17]
	ds_read_b128 v[80:83], v0 offset:18496
	ds_read_b128 v[84:87], v56 offset:64
	ds_read_b128 v[88:91], v56 offset:96
	ds_read_b128 v[96:99], v0 offset:18528
	s_waitcnt lgkmcnt(2)
	v_mfma_f32_32x32x16_bf16 v[18:33], v[80:83], v[84:87], v[18:33]
	ds_read_b128 v[84:87], v56 offset:4672
	ds_read_b128 v[100:103], v56 offset:4704
	s_waitcnt lgkmcnt(1)
	v_mfma_f32_32x32x16_bf16 v[2:17], v[80:83], v[84:87], v[2:17]
	v_mfma_f32_32x32x16_bf16 v[18:33], v[96:99], v[88:91], v[18:33]
	global_load_dwordx4 v[80:83], v[36:37], off offset:1920
	s_nop 0
	global_load_dwordx4 v[36:39], v[38:39], off offset:1920
	s_nop 0
	global_load_dwordx4 v[84:87], v[34:35], off offset:1920
	global_load_dwordx4 v[88:91], v[48:49], off offset:1920
	s_nop 0
	global_load_dwordx4 v[46:49], v[46:47], off offset:1920
	s_nop 0
	global_load_dwordx4 v[140:143], v[40:41], off offset:1920
	s_nop 0
	global_load_dwordx4 v[40:43], v[42:43], off offset:1920
	s_nop 0
	global_load_dwordx4 v[144:147], v[44:45], off offset:1920
	s_waitcnt vmcnt(21)
	ds_write_b128 v54, v[92:95] offset:36864
	ds_write_b128 v54, v[60:63] offset:41472
	ds_write_b128 v54, v[64:67] offset:46080
	s_waitcnt vmcnt(19)
	ds_write_b128 v54, v[128:131] offset:50688
	ds_write_b128 v54, v[124:127] offset:55296
	s_waitcnt vmcnt(18)
	ds_write_b128 v54, v[132:135] offset:59904
	s_waitcnt vmcnt(17)
	ds_write_b128 v54, v[136:139] offset:64512
	s_waitcnt vmcnt(16)
	ds_write_b128 v57, v[164:167] offset:32256
	s_waitcnt lgkmcnt(0)
	s_barrier
	v_mfma_f32_32x32x16_bf16 v[2:17], v[96:99], v[100:103], v[2:17]
	ds_read_b128 v[60:63], v0 offset:55296
	ds_read_b128 v[64:67], v56 offset:36864
	ds_read_b128 v[92:95], v56 offset:36896
	ds_read_b128 v[96:99], v0 offset:55328
	s_waitcnt lgkmcnt(2)
	v_mfma_f32_32x32x16_bf16 v[18:33], v[60:63], v[64:67], v[18:33]
	ds_read_b128 v[64:67], v56 offset:41472
	ds_read_b128 v[100:103], v56 offset:41504
	s_waitcnt lgkmcnt(1)
	v_mfma_f32_32x32x16_bf16 v[2:17], v[60:63], v[64:67], v[2:17]
	v_mfma_f32_32x32x16_bf16 v[18:33], v[96:99], v[92:95], v[18:33]
	s_waitcnt lgkmcnt(0)
	v_mfma_f32_32x32x16_bf16 v[2:17], v[96:99], v[100:103], v[2:17]
	ds_read_b128 v[60:63], v0 offset:55360
	ds_read_b128 v[64:67], v56 offset:36928
	ds_read_b128 v[92:95], v56 offset:36960
	ds_read_b128 v[96:99], v0 offset:55392
	s_waitcnt lgkmcnt(2)
	v_mfma_f32_32x32x16_bf16 v[18:33], v[60:63], v[64:67], v[18:33]
	ds_read_b128 v[64:67], v56 offset:41536
	ds_read_b128 v[100:103], v56 offset:41568
	s_waitcnt vmcnt(13)
	ds_write_b128 v54, v[76:79]
	ds_write_b128 v54, v[68:71] offset:4608
	ds_write_b128 v54, v[72:75] offset:9216
	s_waitcnt vmcnt(11)
	ds_write_b128 v54, v[108:111] offset:13824
	ds_write_b128 v54, v[104:107] offset:18432
	s_waitcnt vmcnt(10)
	ds_write_b128 v54, v[112:115] offset:23040
	s_waitcnt vmcnt(9)
	ds_write_b128 v54, v[116:119] offset:27648
	s_waitcnt vmcnt(8)
	ds_write_b128 v54, v[120:123] offset:32256
	s_waitcnt lgkmcnt(0)
	s_barrier
	v_mfma_f32_32x32x16_bf16 v[2:17], v[60:63], v[64:67], v[2:17]
	ds_read_b128 v[60:63], v0 offset:18432
	ds_read_b128 v[64:67], v56
	ds_read_b128 v[68:71], v56 offset:32
	ds_read_b128 v[72:75], v0 offset:18464
	v_mfma_f32_32x32x16_bf16 v[18:33], v[96:99], v[92:95], v[18:33]
	v_mfma_f32_32x32x16_bf16 v[2:17], v[96:99], v[100:103], v[2:17]
	s_waitcnt lgkmcnt(2)
	v_mfma_f32_32x32x16_bf16 v[18:33], v[60:63], v[64:67], v[18:33]
	ds_read_b128 v[64:67], v56 offset:4608
	ds_read_b128 v[76:79], v56 offset:4640
	s_waitcnt lgkmcnt(1)
	v_mfma_f32_32x32x16_bf16 v[2:17], v[60:63], v[64:67], v[2:17]
	v_mfma_f32_32x32x16_bf16 v[18:33], v[72:75], v[68:71], v[18:33]
	s_waitcnt lgkmcnt(0)
	v_mfma_f32_32x32x16_bf16 v[2:17], v[72:75], v[76:79], v[2:17]
	ds_read_b128 v[60:63], v0 offset:18496
	ds_read_b128 v[64:67], v56 offset:64
	ds_read_b128 v[68:71], v56 offset:96
	ds_read_b128 v[72:75], v0 offset:18528
	s_waitcnt lgkmcnt(2)
	v_mfma_f32_32x32x16_bf16 v[18:33], v[60:63], v[64:67], v[18:33]
	ds_read_b128 v[64:67], v56 offset:4672
	ds_read_b128 v[76:79], v56 offset:4704
	s_waitcnt vmcnt(5)
	ds_write_b128 v54, v[84:87] offset:36864
	ds_write_b128 v54, v[80:83] offset:41472
	ds_write_b128 v54, v[36:39] offset:46080
	s_waitcnt vmcnt(3)
	ds_write_b128 v54, v[46:49] offset:50688
	ds_write_b128 v54, v[88:91] offset:55296
	s_waitcnt vmcnt(2)
	ds_write_b128 v54, v[140:143] offset:59904
	s_waitcnt vmcnt(1)
	ds_write_b128 v54, v[40:43] offset:64512
	s_waitcnt vmcnt(0)
	ds_write_b128 v58, v[144:147]
	s_waitcnt lgkmcnt(0)
	s_barrier
	ds_read_b128 v[34:37], v0 offset:55296
	ds_read_b128 v[38:41], v56 offset:36864
	ds_read_b128 v[42:45], v56 offset:36896
	ds_read_b128 v[46:49], v0 offset:55328
	v_mfma_f32_32x32x16_bf16 v[2:17], v[60:63], v[64:67], v[2:17]
	v_mfma_f32_32x32x16_bf16 v[18:33], v[72:75], v[68:71], v[18:33]
	v_mfma_f32_32x32x16_bf16 v[2:17], v[72:75], v[76:79], v[2:17]
	s_waitcnt lgkmcnt(2)
	v_mfma_f32_32x32x16_bf16 v[18:33], v[34:37], v[38:41], v[18:33]
	ds_read_b128 v[38:41], v56 offset:41472
	ds_read_b128 v[58:61], v56 offset:41504
	s_waitcnt lgkmcnt(1)
	v_mfma_f32_32x32x16_bf16 v[2:17], v[34:37], v[38:41], v[2:17]
	v_mfma_f32_32x32x16_bf16 v[18:33], v[46:49], v[42:45], v[18:33]
	s_waitcnt lgkmcnt(0)
	v_mfma_f32_32x32x16_bf16 v[2:17], v[46:49], v[58:61], v[2:17]
	ds_read_b128 v[34:37], v0 offset:55360
	ds_read_b128 v[38:41], v56 offset:36928
	ds_read_b128 v[42:45], v56 offset:36960
	ds_read_b128 v[46:49], v0 offset:55392
	s_waitcnt lgkmcnt(2)
	v_mfma_f32_32x32x16_bf16 v[18:33], v[34:37], v[38:41], v[18:33]
	ds_read_b128 v[38:41], v56 offset:41536
	ds_read_b128 v[56:59], v56 offset:41568
	s_waitcnt lgkmcnt(0)
	s_barrier
	v_mfma_f32_32x32x16_bf16 v[2:17], v[34:37], v[38:41], v[2:17]
	v_mfma_f32_32x32x16_bf16 v[18:33], v[46:49], v[42:45], v[18:33]
	v_add_u32_e32 v42, v51, v55
	v_add_u32_e32 v37, 0x4000, v42
	v_cmp_gt_i32_e32 vcc, s2, v37
	v_cmp_lt_i32_e64 s[38:39], s24, v37
	v_mfma_f32_32x32x16_bf16 v[2:17], v[46:49], v[56:59], v[2:17]
	s_and_saveexec_b64 s[0:1], s[38:39]
	s_xor_b64 s[2:3], exec, s[0:1]
	v_and_b32_e32 v0, 0xdf, v37
	v_lshrrev_b32_e32 v44, 8, v42
	v_or_b32_e32 v0, 0x2000, v0
	s_or_saveexec_b64 s[2:3], s[2:3]
	v_lshrrev_b32_e32 v38, 2, v37
	v_mov_b32_e32 v34, 0
	v_ashrrev_i32_e32 v36, 13, v37
	v_and_b32_e32 v43, 0x7f0, v38
	v_mov_b32_e32 v35, 0
	s_xor_b64 exec, exec, s[2:3]
	v_ashrrev_i32_e32 v44, 13, v37
	v_and_b32_e32 v0, 0x1fdf, v37
	v_and_b32_e32 v34, 0x7f0, v38
	v_lshlrev_b32_e32 v35, 4, v53
	s_or_b64 exec, exec, s[2:3]
	v_bfe_u32 v37, v52, 5, 1
	v_lshlrev_b32_e32 v38, 3, v37
	v_and_b32_e32 v45, 64, v52
	v_or_b32_e32 v39, 2, v38
	v_or_b32_e32 v40, 4, v38
	v_or_b32_e32 v41, 6, v38
	v_lshlrev_b32_e32 v37, 2, v37
	v_cmp_eq_u32_e64 s[38:39], 0, v45
	s_and_saveexec_b64 s[2:3], s[38:39]
	s_cbranch_execz .LBB0_564
	s_and_saveexec_b64 s[22:23], vcc
	s_cbranch_execz .LBB0_563
	v_or_b32_e32 v45, v34, v38
	v_or_b32_e32 v46, v34, v39
	v_or_b32_e32 v52, v34, v40
	v_or_b32_e32 v53, v34, v41
	v_lshlrev_b32_e32 v34, 3, v45
	v_or_b32_e32 v54, v35, v38
	v_or_b32_e32 v55, v35, v39
	v_or_b32_e32 v56, v35, v40
	v_or_b32_e32 v57, v35, v41
	v_lshlrev_b32_e32 v45, 3, v46
	global_load_dwordx2 v[34:35], v34, s[80:81]
	s_nop 0
	global_load_dwordx2 v[46:47], v45, s[80:81]
	v_lshlrev_b32_e32 v45, 3, v53
	s_waitcnt vmcnt(1)
	v_mov_b32_e32 v48, v34
	s_waitcnt vmcnt(0)
	v_mov_b32_e32 v49, v46
	v_mov_b32_e32 v46, v35
	v_mul_f32_e32 v34, v26, v46
	v_mul_f32_e32 v35, v27, v47
	s_nop 0
	v_fma_f32 v34, v18, v48, -v34
	v_fma_f32 v35, v19, v49, -v35
	v_mul_f32_e32 v18, v18, v46
	v_mul_f32_e32 v19, v19, v47
	s_nop 0
	v_fma_f32 v26, v26, v48, v18
	v_fma_f32 v27, v27, v49, v19
	v_lshlrev_b32_e32 v18, 3, v52
	global_load_dwordx2 v[18:19], v18, s[80:81]
	s_nop 0
	global_load_dwordx2 v[46:47], v45, s[80:81]
	s_waitcnt vmcnt(1)
	v_mov_b32_e32 v48, v18
	s_waitcnt vmcnt(0)
	v_mov_b32_e32 v49, v46
	v_mov_b32_e32 v46, v19
	v_mul_f32_e32 v18, v28, v46
	v_mul_f32_e32 v19, v29, v47
	s_nop 0
	v_fma_f32 v52, v20, v48, -v18
	v_fma_f32 v53, v21, v49, -v19
	v_mul_f32_e32 v18, v20, v46
	v_mul_f32_e32 v19, v21, v47
	v_lshlrev_b32_e32 v20, 3, v55
	v_fma_f32 v28, v28, v48, v18
	v_fma_f32 v29, v29, v49, v19
	v_lshlrev_b32_e32 v18, 3, v54
	global_load_dwordx2 v[18:19], v18, s[80:81]
	s_nop 0
	global_load_dwordx2 v[20:21], v20, s[80:81]
	s_waitcnt vmcnt(1)
	v_mov_b32_e32 v46, v18
	s_waitcnt vmcnt(0)
	v_mov_b32_e32 v47, v20
	v_mov_b32_e32 v20, v19
	v_mul_f32_e32 v18, v30, v20
	v_mul_f32_e32 v19, v31, v21
	s_nop 0
	v_fma_f32 v48, v22, v46, -v18
	v_fma_f32 v49, v23, v47, -v19
	v_mul_f32_e32 v18, v22, v20
	v_mul_f32_e32 v19, v23, v21
	v_lshlrev_b32_e32 v20, 3, v56
	v_fma_f32 v30, v30, v46, v18
	v_fma_f32 v31, v31, v47, v19
	v_lshlrev_b32_e32 v18, 3, v57
	global_load_dwordx2 v[18:19], v18, s[80:81]
	s_nop 0
	global_load_dwordx2 v[20:21], v20, s[80:81]
	s_waitcnt vmcnt(1)
	v_mov_b32_e32 v47, v19
	s_waitcnt vmcnt(0)
	v_mov_b32_e32 v46, v21
	v_mov_b32_e32 v22, v20
	v_mov_b32_e32 v23, v18
	v_mul_f32_e32 v46, v32, v46
	v_mul_f32_e32 v47, v33, v47
	v_mul_f32_e32 v20, v32, v20
	v_fma_f32 v46, v24, v22, -v46
	v_fma_f32 v47, v25, v23, -v47
	v_mul_f32_e32 v22, v24, v21
	v_mov_b32_e32 v24, v33
	v_mul_f32_e32 v18, v24, v18
	v_mul_f32_e32 v19, v25, v19
	v_mov_b32_e32 v24, v46
	v_mov_b32_e32 v21, v18
	v_mov_b32_e32 v23, v19
	v_add_f32_e32 v32, v20, v22
	v_add_f32_e32 v33, v21, v23
	v_mov_b32_e32 v18, v34
	v_mov_b32_e32 v19, v35
	v_mov_b32_e32 v20, v52
	v_mov_b32_e32 v21, v53
	v_mov_b32_e32 v22, v48
	v_mov_b32_e32 v23, v49
	v_mov_b32_e32 v25, v47
.LBB0_563:
	s_or_b64 exec, exec, s[22:23]
	v_mul_lo_u32 v34, v44, 6
	v_cvt_pk_bf16_f32 v18, v18, v19
	v_cvt_pk_bf16_f32 v19, v20, v21
	v_cvt_pk_bf16_f32 v20, v22, v23
	v_cvt_pk_bf16_f32 v22, v26, v27
	v_cvt_pk_bf16_f32 v23, v28, v29
	v_mad_i64_i32 v[26:27], s[0:1], v34, s25, v[0:1]
	v_mov_b64_e32 v[28:29], s[36:37]
	v_cvt_pk_bf16_f32 v21, v24, v25
	v_cvt_pk_bf16_f32 v24, v30, v31
	v_mad_u64_u32 v[30:31], s[0:1], v26, s5, v[28:29]
	v_mad_i32_i24 v31, v27, s5, v31
	v_lshlrev_b32_e32 v26, 1, v37
	v_mov_b32_e32 v27, v1
	v_lshl_add_u64 v[30:31], v[30:31], 0, v[26:27]
	v_cvt_pk_bf16_f32 v25, v32, v33
	v_lshl_add_u64 v[32:33], v[30:31], 0, s[8:9]
	v_add_co_u32_e32 v30, vcc, s47, v30
	s_nop 1
	v_addc_co_u32_e32 v31, vcc, 0, v31, vcc
	s_nop 1
	v_permlane32_swap_b32 v18, v20
	v_permlane32_swap_b32 v19, v21
	v_permlane32_swap_b32 v22, v24
	v_permlane32_swap_b32 v23, v25
	v_lshl_add_u64 v[250:251], v[32:33], 0, v[248:249]
	global_store_dwordx4 v[250:251], v[18:21], off
	global_store_dwordx4 v[250:251], v[22:25], off offset:32
	v_or_b32_e32 v30, 1, v34
	v_mad_i64_i32 v[30:31], s[0:1], v30, s25, v[0:1]
	v_mad_u64_u32 v[32:33], s[0:1], v30, s5, v[28:29]
	v_mad_i32_i24 v33, v31, s5, v33
	v_lshl_add_u64 v[30:31], v[32:33], 0, v[26:27]
	v_lshl_add_u64 v[32:33], v[30:31], 0, s[8:9]
	v_add_co_u32_e32 v30, vcc, s47, v30
	s_nop 1
	v_addc_co_u32_e32 v31, vcc, 0, v31, vcc
	v_lshl_add_u64 v[250:251], v[32:33], 0, v[248:249]
	global_store_dwordx4 v[250:251], v[18:21], off
	global_store_dwordx4 v[250:251], v[22:25], off offset:32
	v_add_u32_e32 v30, 2, v34
	v_mad_i64_i32 v[30:31], s[0:1], v30, s25, v[0:1]
	v_mad_u64_u32 v[32:33], s[0:1], v30, s5, v[28:29]
	v_mad_i32_i24 v33, v31, s5, v33
	v_lshl_add_u64 v[30:31], v[32:33], 0, v[26:27]
	v_lshl_add_u64 v[32:33], v[30:31], 0, s[8:9]
	v_add_co_u32_e32 v30, vcc, s47, v30
	s_nop 1
	v_addc_co_u32_e32 v31, vcc, 0, v31, vcc
	v_lshl_add_u64 v[250:251], v[32:33], 0, v[248:249]
	global_store_dwordx4 v[250:251], v[18:21], off
	global_store_dwordx4 v[250:251], v[22:25], off offset:32
	v_add_u32_e32 v30, 3, v34
	v_mad_i64_i32 v[30:31], s[0:1], v30, s25, v[0:1]
	v_mad_u64_u32 v[32:33], s[0:1], v30, s5, v[28:29]
	v_mad_i32_i24 v33, v31, s5, v33
	v_lshl_add_u64 v[30:31], v[32:33], 0, v[26:27]
	v_lshl_add_u64 v[32:33], v[30:31], 0, s[8:9]
	v_add_co_u32_e32 v30, vcc, s47, v30
	s_nop 1
	v_addc_co_u32_e32 v31, vcc, 0, v31, vcc
	v_lshl_add_u64 v[250:251], v[32:33], 0, v[248:249]
	global_store_dwordx4 v[250:251], v[18:21], off
	global_store_dwordx4 v[250:251], v[22:25], off offset:32
	v_add_u32_e32 v30, 4, v34
	v_mad_i64_i32 v[30:31], s[0:1], v30, s25, v[0:1]
	v_mad_u64_u32 v[32:33], s[0:1], v30, s5, v[28:29]
	v_mad_i32_i24 v33, v31, s5, v33
	v_lshl_add_u64 v[30:31], v[32:33], 0, v[26:27]
	v_lshl_add_u64 v[32:33], v[30:31], 0, s[8:9]
	v_add_co_u32_e32 v30, vcc, s47, v30
	s_nop 1
	v_addc_co_u32_e32 v31, vcc, 0, v31, vcc
	v_lshl_add_u64 v[250:251], v[32:33], 0, v[248:249]
	global_store_dwordx4 v[250:251], v[18:21], off
	global_store_dwordx4 v[250:251], v[22:25], off offset:32
	v_add_u32_e32 v30, 5, v34
	v_mad_i64_i32 v[30:31], s[0:1], v30, s25, v[0:1]
	v_mad_u64_u32 v[28:29], s[0:1], v30, s5, v[28:29]
	v_mad_i32_i24 v29, v31, s5, v29
	v_lshl_add_u64 v[26:27], v[28:29], 0, v[26:27]
	v_lshl_add_u64 v[28:29], v[26:27], 0, s[8:9]
	v_add_co_u32_e32 v26, vcc, 0x917d000, v26
	s_nop 1
	v_addc_co_u32_e32 v27, vcc, 0, v27, vcc
	v_lshl_add_u64 v[250:251], v[28:29], 0, v[248:249]
	global_store_dwordx4 v[250:251], v[18:21], off
	global_store_dwordx4 v[250:251], v[22:25], off offset:32
